# GEMM blocks raise wave priority only after the initial fragment reads
# speedup vs baseline: 1.0034x; 1.0034x over previous
; __device__ __forceinline__ int opaque_tid() { int t = threadIdx.x; asm volatile("" : "+v"(t)); return t; }
; __device__ __forceinline__ void gemm_kstep(const u16* sb, int wn, int wt, int r, int h, f32x16 (&acc)[2][2]) {
;   const u16* bw = sb + (wn * 64 + r) * LDT + h * 8;
;   const u16* bx = sb + TILE_U16 + (wt * 64 + r) * LDT + h * 8;
;   __builtin_amdgcn_s_setprio(1);
; #pragma unroll
;   for (int ks = 0; ks < 4; ++ks) {
;     bf16x8 a0 = *(const bf16x8*)(bw + ks * 16);
;     bf16x8 a1 = *(const bf16x8*)(bw + 32 * LDT + ks * 16);
;     bf16x8 b0 = *(const bf16x8*)(bx + ks * 16);
;     bf16x8 b1 = *(const bf16x8*)(bx + 32 * LDT + ks * 16);
;     acc[0][0] = mfma32(a0, b0, acc[0][0]);
;     acc[0][1] = mfma32(a0, b1, acc[0][1]);
;     acc[1][0] = mfma32(a1, b0, acc[1][0]);
;     acc[1][1] = mfma32(a1, b1, acc[1][1]);
;   }
;   __builtin_amdgcn_s_setprio(0);
; }
; __device__ __forceinline__ void stage_bf16(u16* st, f32x16 (&acc)[2][2]) {
;   const int tid = opaque_tid(), lane = tid & 63, w = tid >> 6, r = lane & 31, h = lane >> 5;
;   const int wn = w >> 1, wt = w & 1;
; #pragma unroll
;   for (int nb = 0; nb < 2; ++nb)
; #pragma unroll
;     for (int tb = 0; tb < 2; ++tb) {
;       const int token = wt * 64 + tb * 32 + r;
; #pragma unroll
;       for (int g = 0; g < 4; ++g) {
;         const int n0 = wn * 64 + nb * 32 + 8 * g + 4 * h;
;         uint2 v;
;         v.x = pack2(acc[nb][tb][4 * g], acc[nb][tb][4 * g + 1]);
;         v.y = pack2(acc[nb][tb][4 * g + 2], acc[nb][tb][4 * g + 3]);
;         *(uint2*)(st + token * 136 + n0) = v;
;       }
;     }
; }
; __device__ void gemm_phase(const u16* __restrict__ Wb, int ldw, const u16* __restrict__ Xb, int ldx, int K,
;                            u16* __restrict__ outb, int ldo, int ntn, int ntiles, u16* lds) {
;     ...
;       gemm_kstep(lds + 2 * TILE_U16, wn, wt, r, h, acc);
;       if (kt + 2 < nk) gs_store(B, lds, lo);
;       __syncthreads();
;     }
;     stage_bf16(lds, acc);
;     __syncthreads();
;     u16* out = outb + (size_t)GP_MT(q) * 128 * ldo + GP_NT(q) * 128;
; #pragma unroll
;     for (int i = 0; i < 8; ++i) {
;       const int id = tid + 256 * i;
;       const int row = id >> 4, c = id & 15;
;       uint4 v = *(const uint4*)(lds + row * 136 + c * 8);
;       *(uint4*)(out + (size_t)row * ldo + c * 8) = v;
;     }
;     __syncthreads();
.LBB0_597:
	ds_read_b128 v[158:161], v140 offset:36864
	ds_read_b128 v[162:165], v141 offset:55296
	ds_read_b128 v[166:169], v141 offset:59904
	ds_read_b128 v[214:217], v140 offset:41472
	ds_read_b128 v[218:221], v140 offset:36896
	ds_read_b128 v[222:225], v141 offset:55328
	ds_read_b128 v[226:229], v141 offset:59936
	ds_read_b128 v[230:233], v140 offset:41504
	s_setprio 1
	s_waitcnt lgkmcnt(4)
	v_mfma_f32_32x32x16_bf16 v[50:65], v[158:161], v[162:165], v[50:65]
	v_mfma_f32_32x32x16_bf16 v[34:49], v[158:161], v[166:169], v[34:49]
	v_mfma_f32_32x32x16_bf16 v[18:33], v[214:217], v[162:165], v[18:33]
	v_mfma_f32_32x32x16_bf16 v[2:17], v[214:217], v[166:169], v[2:17]
	ds_read_b128 v[158:161], v140 offset:36928
	ds_read_b128 v[162:165], v141 offset:55360
	ds_read_b128 v[166:169], v141 offset:59968
	ds_read_b128 v[214:217], v140 offset:41536
	s_waitcnt lgkmcnt(4)
	v_mfma_f32_32x32x16_bf16 v[50:65], v[218:221], v[222:225], v[50:65]
	v_mfma_f32_32x32x16_bf16 v[34:49], v[218:221], v[226:229], v[34:49]
	v_mfma_f32_32x32x16_bf16 v[18:33], v[230:233], v[222:225], v[18:33]
	v_mfma_f32_32x32x16_bf16 v[2:17], v[230:233], v[226:229], v[2:17]
	ds_read_b128 v[218:221], v140 offset:36960
	ds_read_b128 v[222:225], v141 offset:55392
	ds_read_b128 v[226:229], v141 offset:60000
	ds_read_b128 v[230:233], v140 offset:41568
	s_waitcnt lgkmcnt(4)
	v_mfma_f32_32x32x16_bf16 v[50:65], v[158:161], v[162:165], v[50:65]
	v_mfma_f32_32x32x16_bf16 v[34:49], v[158:161], v[166:169], v[34:49]
	v_mfma_f32_32x32x16_bf16 v[18:33], v[214:217], v[162:165], v[18:33]
	v_mfma_f32_32x32x16_bf16 v[2:17], v[214:217], v[166:169], v[2:17]
	s_waitcnt lgkmcnt(0)
	v_mfma_f32_32x32x16_bf16 v[50:65], v[218:221], v[222:225], v[50:65]
	v_mfma_f32_32x32x16_bf16 v[34:49], v[218:221], v[226:229], v[34:49]
	v_mfma_f32_32x32x16_bf16 v[18:33], v[230:233], v[222:225], v[18:33]
	v_mfma_f32_32x32x16_bf16 v[2:17], v[230:233], v[226:229], v[2:17]
	s_setprio 0
	s_and_b32 s0, s39, 0xffff
	s_mul_i32 s0, s0, 0xe38f
	s_lshr_b32 s0, s0, 23
	v_mov_b32_e32 v158, v174
	s_lshl_b32 s1, s0, 3
	s_mulk_i32 s0, 0x90
	s_barrier
	s_sub_i32 s0, s39, s0
	v_lshrrev_b32_e32 v160, 2, v158
	v_and_b32_e32 v160, 8, v160
	s_add_i32 s1, s18, s1
	s_and_b32 s39, s0, 0xffff
	s_and_b32 s0, s0, 7
	v_and_b32_e32 v159, 0x5f, v158
	v_and_or_b32 v158, v158, s29, v160
	s_or_b32 s0, s1, s0
	v_mad_u32_u24 v158, v159, s28, v158
	s_mul_hi_u32 s1, s0, 0x90000
	s_mul_i32 s0, s0, 0x90000
	v_cvt_pk_bf16_f32 v53, v52, v53
	v_cvt_pk_bf16_f32 v52, v50, v51
	v_cvt_pk_bf16_f32 v51, v56, v57
	v_cvt_pk_bf16_f32 v50, v54, v55
	v_cvt_pk_bf16_f32 v37, v36, v37
	v_cvt_pk_bf16_f32 v36, v34, v35
	v_cvt_pk_bf16_f32 v35, v40, v41
	v_cvt_pk_bf16_f32 v34, v38, v39
	v_add_u32_e32 v38, 0x2000, v158
	v_cvt_pk_bf16_f32 v21, v20, v21
	v_cvt_pk_bf16_f32 v20, v18, v19
	v_cvt_pk_bf16_f32 v19, v24, v25
	v_cvt_pk_bf16_f32 v18, v22, v23
	v_cvt_pk_bf16_f32 v5, v4, v5
	v_cvt_pk_bf16_f32 v4, v2, v3
	v_cvt_pk_bf16_f32 v3, v8, v9
	v_cvt_pk_bf16_f32 v2, v6, v7
	s_add_u32 s0, s42, s0
	ds_write2_b64 v158, v[52:53], v[50:51] offset1:2
	v_cvt_pk_bf16_f32 v51, v60, v61
	v_cvt_pk_bf16_f32 v50, v58, v59
	v_cvt_pk_bf16_f32 v53, v64, v65
	v_cvt_pk_bf16_f32 v52, v62, v63
	ds_write2_b64 v38, v[36:37], v[34:35] offset0:64 offset1:66
	v_cvt_pk_bf16_f32 v35, v44, v45
	v_cvt_pk_bf16_f32 v34, v42, v43
	v_cvt_pk_bf16_f32 v37, v48, v49
	v_cvt_pk_bf16_f32 v36, v46, v47
	ds_write2_b64 v158, v[20:21], v[18:19] offset0:8 offset1:10
	v_cvt_pk_bf16_f32 v19, v28, v29
	v_cvt_pk_bf16_f32 v18, v26, v27
	v_cvt_pk_bf16_f32 v21, v32, v33
	v_cvt_pk_bf16_f32 v20, v30, v31
	ds_write2_b64 v38, v[4:5], v[2:3] offset0:72 offset1:74
	v_cvt_pk_bf16_f32 v3, v12, v13
	v_cvt_pk_bf16_f32 v2, v10, v11
	v_cvt_pk_bf16_f32 v5, v16, v17
	v_cvt_pk_bf16_f32 v4, v14, v15
	s_addc_u32 s1, s43, s1
	s_lshl_b32 s39, s39, 5
	ds_write2_b64 v158, v[50:51], v[52:53] offset0:4 offset1:6
	ds_write2_b64 v38, v[34:35], v[36:37] offset0:68 offset1:70
	ds_write2_b64 v158, v[18:19], v[20:21] offset0:12 offset1:14
	ds_write2_b64 v38, v[2:3], v[4:5] offset0:76 offset1:78
	s_waitcnt lgkmcnt(0)
	s_barrier
	s_and_b32 s39, s39, 0x1f00
	ds_read_b128 v[2:5], v190
	ds_read_b128 v[6:9], v191
	s_add_u32 s0, s0, s39
	s_addc_u32 s1, s1, 0
	v_lshl_add_u64 v[14:15], s[0:1], 0, v[0:1]
	v_lshl_add_u64 v[10:11], v[14:15], 0, v[142:143]
	s_waitcnt lgkmcnt(1)
	global_store_dwordx4 v[10:11], v[2:5], off
	ds_read_b128 v[2:5], v192
	v_lshl_add_u64 v[10:11], v[14:15], 0, v[144:145]
	s_waitcnt lgkmcnt(1)
	global_store_dwordx4 v[10:11], v[6:9], off
	ds_read_b128 v[6:9], v193
	v_lshl_add_u64 v[10:11], v[14:15], 0, v[146:147]
	s_waitcnt lgkmcnt(1)
	global_store_dwordx4 v[10:11], v[2:5], off
	ds_read_b128 v[2:5], v194
	v_lshl_add_u64 v[10:11], v[14:15], 0, v[148:149]
	s_waitcnt lgkmcnt(1)
	global_store_dwordx4 v[10:11], v[6:9], off
	v_lshl_add_u64 v[10:11], v[14:15], 0, v[150:151]
	ds_read_b128 v[6:9], v195
	s_waitcnt lgkmcnt(1)
	global_store_dwordx4 v[10:11], v[2:5], off
	ds_read_b128 v[2:5], v196
	ds_read_b128 v[10:13], v197
	v_lshl_add_u64 v[16:17], v[14:15], 0, v[152:153]
	s_waitcnt lgkmcnt(2)
	global_store_dwordx4 v[16:17], v[6:9], off
	s_and_b64 vcc, exec, s[16:17]
	s_mov_b32 s39, s38
	v_lshl_add_u64 v[6:7], v[14:15], 0, v[154:155]
	s_waitcnt lgkmcnt(1)
	global_store_dwordx4 v[6:7], v[2:5], off
	s_nop 1
	v_lshl_add_u64 v[2:3], v[14:15], 0, v[156:157]
	s_waitcnt lgkmcnt(0)
	global_store_dwordx4 v[2:3], v[10:13], off
	s_barrier
	s_cbranch_vccnz .LBB0_602
; __device__ __forceinline__ void gemm_kstep(const u16* sb, int wn, int wt, int r, int h, f32x16 (&acc)[2][2]) {
;   const u16* bw = sb + (wn * 64 + r) * LDT + h * 8;
;   const u16* bx = sb + TILE_U16 + (wt * 64 + r) * LDT + h * 8;
;   __builtin_amdgcn_s_setprio(1);
; #pragma unroll
;   for (int ks = 0; ks < 4; ++ks) {
;     bf16x8 a0 = *(const bf16x8*)(bw + ks * 16);
;     bf16x8 a1 = *(const bf16x8*)(bw + 32 * LDT + ks * 16);
;     bf16x8 b0 = *(const bf16x8*)(bx + ks * 16);
;     bf16x8 b1 = *(const bf16x8*)(bx + 32 * LDT + ks * 16);
;     acc[0][0] = mfma32(a0, b0, acc[0][0]);
;     acc[0][1] = mfma32(a0, b1, acc[0][1]);
;     acc[1][0] = mfma32(a1, b0, acc[1][0]);
;     acc[1][1] = mfma32(a1, b1, acc[1][1]);
;   }
;   __builtin_amdgcn_s_setprio(0);
; }
; __device__ void gemm_phase(const u16* __restrict__ Wb, int ldw, const u16* __restrict__ Xb, int ldx, int K,
;                            u16* __restrict__ outb, int ldo, int ntn, int ntiles, u16* lds) {
;     ...
;   for (; q < L; q += nbl) {
;     const int qn = q + nbl;
;     const bool has_next = qn < L;
;     const int qq = has_next ? qn : q;
;     const u16* gwn = Wb + (size_t)(GP_NT(qq) * 128 + lrow) * ldw + lc * 8;
;     const u16* gxn = Xb + (size_t)(GP_MT(qq) * 128 + lrow) * ldx + lc * 8;
;     f32x16 acc[2][2];
; #pragma unroll
;     for (int a = 0; a < 2; ++a)
; #pragma unroll
;       for (int b = 0; b < 2; ++b)
; #pragma unroll
;         for (int i = 0; i < 16; ++i) acc[a][b][i] = 0.f;
;     gs_store(B, lds, lo);
;     __syncthreads();
;     for (int kt = 0; kt < nk; kt += 2) {
;       if (kt + 2 < nk) gs_load(B, gw, ldw, gx, ldx, (kt + 2) * 64);
;       else if (has_next) gs_load(B, gwn, ldw, gxn, ldx, 0);
;       gemm_kstep(lds, wn, wt, r, h, acc);
;       gs_store(A, lds + 2 * TILE_U16, lo);
;       __syncthreads();
.LBB0_598:
	v_mov_b64_e32 v[160:161], v[132:133]
	v_add_co_u32_e32 v162, vcc, s81, v160
	v_mov_b64_e32 v[158:159], v[134:135]
	s_nop 0
	v_addc_co_u32_e32 v163, vcc, 0, v161, vcc
	v_add_co_u32_e32 v164, vcc, s80, v160
	s_waitcnt vmcnt(1)
	ds_write_b128 v188, v[98:101]
	ds_write_b128 v188, v[102:105] offset:4608
	ds_write_b128 v188, v[106:109] offset:9216
	ds_write_b128 v188, v[110:113] offset:13824
	ds_write_b128 v188, v[114:117] offset:18432
	ds_write_b128 v188, v[118:121] offset:23040
	ds_write_b128 v188, v[122:125] offset:27648
	ds_write_b128 v188, v[126:129] offset:32256
	v_addc_co_u32_e32 v165, vcc, 0, v161, vcc
	v_add_co_u32_e32 v166, vcc, s84, v160
	s_waitcnt lgkmcnt(0)
	s_nop 0
	v_addc_co_u32_e32 v167, vcc, 0, v161, vcc
	v_add_co_u32_e32 v168, vcc, s81, v158
	s_barrier
	s_nop 0
	v_addc_co_u32_e32 v169, vcc, 0, v159, vcc
	v_add_co_u32_e32 v170, vcc, s80, v158
	s_nop 1
	v_addc_co_u32_e32 v171, vcc, 0, v159, vcc
	v_add_co_u32_e32 v172, vcc, s84, v158
	global_load_dwordx4 v[98:101], v[160:161], off offset:256
	global_load_dwordx4 v[102:105], v[162:163], off offset:256
	v_addc_co_u32_e32 v173, vcc, 0, v159, vcc
	global_load_dwordx4 v[106:109], v[164:165], off offset:256
	global_load_dwordx4 v[110:113], v[166:167], off offset:256
	global_load_dwordx4 v[114:117], v[158:159], off offset:256
	global_load_dwordx4 v[118:121], v[168:169], off offset:256
	global_load_dwordx4 v[122:125], v[170:171], off offset:256
	global_load_dwordx4 v[126:129], v[172:173], off offset:256
	s_add_i32 s38, s39, s87
	s_cmpk_gt_u32 s38, 0x23f
	s_cselect_b64 s[16:17], -1, 0
	s_cmpk_lt_u32 s38, 0x240
	s_cselect_b64 s[0:1], -1, 0
	s_and_b64 s[40:41], s[0:1], exec
	s_cselect_b32 s40, s38, s39
	s_mul_hi_u32 s41, s40, 0x38e38e39
	s_lshr_b32 s41, s41, 5
	s_mul_i32 s44, s41, 0x90
	s_sub_i32 s40, s40, s44
	s_lshl_b32 s44, s40, 4
	s_and_b32 s40, s40, 7
	s_or_b32 s40, s40, s18
	s_lshl_b32 s41, s41, 10
	s_lshl_b32 s40, s40, 7
	s_and_b32 s44, s44, 0xf80
	s_add_i32 s40, s40, s41
	v_add_u32_e32 v2, s44, v131
	v_add_u32_e32 v4, s40, v131
	v_ashrrev_i32_e32 v3, 31, v2
	v_ashrrev_i32_e32 v5, 31, v4
	v_lshlrev_b64 v[2:3], 11, v[2:3]
	v_lshlrev_b64 v[4:5], 11, v[4:5]
	v_lshl_add_u64 v[132:133], v[136:137], 0, v[2:3]
	v_lshl_add_u64 v[134:135], v[138:139], 0, v[4:5]
	s_setprio 1
	ds_read_b128 v[2:5], v140
	ds_read_b128 v[6:9], v141 offset:18432
	ds_read_b128 v[10:13], v141 offset:23040
	s_waitcnt lgkmcnt(1)
	v_mfma_f32_32x32x16_bf16 v[50:65], v[2:5], v[6:9], 0
	s_waitcnt lgkmcnt(0)
	v_mfma_f32_32x32x16_bf16 v[34:49], v[2:5], v[10:13], 0
	ds_read_b128 v[2:5], v140 offset:4608
	ds_read_b128 v[198:201], v140 offset:32
	ds_read_b128 v[202:205], v141 offset:18464
	ds_read_b128 v[206:209], v141 offset:23072
	s_waitcnt lgkmcnt(1)
	v_mfma_f32_32x32x16_bf16 v[50:65], v[198:201], v[202:205], v[50:65]
	s_waitcnt lgkmcnt(0)
	v_mfma_f32_32x32x16_bf16 v[34:49], v[198:201], v[206:209], v[34:49]
	ds_read_b128 v[198:201], v140 offset:4640
	v_mfma_f32_32x32x16_bf16 v[18:33], v[2:5], v[6:9], 0
	v_mfma_f32_32x32x16_bf16 v[2:17], v[2:5], v[10:13], 0
	s_waitcnt lgkmcnt(0)
	v_mfma_f32_32x32x16_bf16 v[18:33], v[198:201], v[202:205], v[18:33]
	v_mfma_f32_32x32x16_bf16 v[2:17], v[198:201], v[206:209], v[2:17]
	ds_read_b128 v[198:201], v140 offset:64
	ds_read_b128 v[202:205], v141 offset:18496
	ds_read_b128 v[206:209], v141 offset:23104
	s_waitcnt lgkmcnt(1)
	v_mfma_f32_32x32x16_bf16 v[50:65], v[198:201], v[202:205], v[50:65]
	s_waitcnt lgkmcnt(0)
	v_mfma_f32_32x32x16_bf16 v[34:49], v[198:201], v[206:209], v[34:49]
	ds_read_b128 v[198:201], v140 offset:4672
	s_waitcnt lgkmcnt(0)
	v_mfma_f32_32x32x16_bf16 v[18:33], v[198:201], v[202:205], v[18:33]
	v_mfma_f32_32x32x16_bf16 v[2:17], v[198:201], v[206:209], v[2:17]
	ds_read_b128 v[198:201], v140 offset:96
	ds_read_b128 v[202:205], v141 offset:18528
	ds_read_b128 v[206:209], v141 offset:23136
	s_waitcnt lgkmcnt(1)
	v_mfma_f32_32x32x16_bf16 v[50:65], v[198:201], v[202:205], v[50:65]
	s_waitcnt lgkmcnt(0)
	v_mfma_f32_32x32x16_bf16 v[34:49], v[198:201], v[206:209], v[34:49]
	ds_read_b128 v[198:201], v140 offset:4704
	s_waitcnt lgkmcnt(0)
	v_mfma_f32_32x32x16_bf16 v[18:33], v[198:201], v[202:205], v[18:33]
	v_mfma_f32_32x32x16_bf16 v[2:17], v[198:201], v[206:209], v[2:17]
	s_setprio 0
	ds_write_b128 v188, v[66:69] offset:36864
	ds_write_b128 v188, v[70:73] offset:41472
	ds_write_b128 v188, v[74:77] offset:46080
	ds_write_b128 v188, v[78:81] offset:50688
	ds_write_b128 v188, v[82:85] offset:55296
	ds_write_b128 v188, v[86:89] offset:59904
	ds_write_b128 v188, v[90:93] offset:64512
	s_waitcnt vmcnt(8)
	ds_write_b128 v189, v[94:97] offset:13824
	s_waitcnt lgkmcnt(0)
	s_barrier
; __device__ __forceinline__ void gemm_kstep(const u16* sb, int wn, int wt, int r, int h, f32x16 (&acc)[2][2]) {
;   const u16* bw = sb + (wn * 64 + r) * LDT + h * 8;
;   const u16* bx = sb + TILE_U16 + (wt * 64 + r) * LDT + h * 8;
;   __builtin_amdgcn_s_setprio(1);
; #pragma unroll
;   for (int ks = 0; ks < 4; ++ks) {
;     bf16x8 a0 = *(const bf16x8*)(bw + ks * 16);
;     bf16x8 a1 = *(const bf16x8*)(bw + 32 * LDT + ks * 16);
;     bf16x8 b0 = *(const bf16x8*)(bx + ks * 16);
;     bf16x8 b1 = *(const bf16x8*)(bx + 32 * LDT + ks * 16);
;     acc[0][0] = mfma32(a0, b0, acc[0][0]);
;     acc[0][1] = mfma32(a0, b1, acc[0][1]);
;     acc[1][0] = mfma32(a1, b0, acc[1][0]);
;     acc[1][1] = mfma32(a1, b1, acc[1][1]);
;   }
;   __builtin_amdgcn_s_setprio(0);
; }
; __device__ void gemm_phase(const u16* __restrict__ Wb, int ldw, const u16* __restrict__ Xb, int ldx, int K,
;                            u16* __restrict__ outb, int ldo, int ntn, int ntiles, u16* lds) {
;     ...
;     for (int kt = 0; kt < nk; kt += 2) {
;       if (kt + 2 < nk) gs_load(B, gw, ldw, gx, ldx, (kt + 2) * 64);
;       else if (has_next) gs_load(B, gwn, ldw, gxn, ldx, 0);
;       gemm_kstep(lds, wn, wt, r, h, acc);
;       gs_store(A, lds + 2 * TILE_U16, lo);
;       __syncthreads();
;       if (kt + 3 < nk) gs_load(A, gw, ldw, gx, ldx, (kt + 3) * 64);
;       else if (has_next) gs_load(A, gwn, ldw, gxn, ldx, 64);
;       gemm_kstep(lds + 2 * TILE_U16, wn, wt, r, h, acc);
;       if (kt + 2 < nk) gs_store(B, lds, lo);
;       __syncthreads();
;     }
	ds_read_b128 v[198:201], v140 offset:36864
	ds_read_b128 v[202:205], v141 offset:55296
	ds_read_b128 v[206:209], v141 offset:59904
	ds_read_b128 v[214:217], v140 offset:41472
	ds_read_b128 v[218:221], v140 offset:36896
	ds_read_b128 v[222:225], v141 offset:55328
	ds_read_b128 v[226:229], v141 offset:59936
	ds_read_b128 v[230:233], v140 offset:41504
	s_setprio 1
	s_waitcnt lgkmcnt(4)
	v_mfma_f32_32x32x16_bf16 v[50:65], v[198:201], v[202:205], v[50:65]
	v_mfma_f32_32x32x16_bf16 v[34:49], v[198:201], v[206:209], v[34:49]
	v_mfma_f32_32x32x16_bf16 v[18:33], v[214:217], v[202:205], v[18:33]
	v_mfma_f32_32x32x16_bf16 v[2:17], v[214:217], v[206:209], v[2:17]
	global_load_dwordx4 v[66:69], v[160:161], off offset:384
	global_load_dwordx4 v[70:73], v[162:163], off offset:384
	global_load_dwordx4 v[74:77], v[164:165], off offset:384
	global_load_dwordx4 v[78:81], v[166:167], off offset:384
	global_load_dwordx4 v[82:85], v[158:159], off offset:384
	global_load_dwordx4 v[86:89], v[168:169], off offset:384
	global_load_dwordx4 v[90:93], v[170:171], off offset:384
	global_load_dwordx4 v[94:97], v[172:173], off offset:384
	ds_read_b128 v[198:201], v140 offset:36928
	ds_read_b128 v[202:205], v141 offset:55360
	ds_read_b128 v[206:209], v141 offset:59968
	ds_read_b128 v[214:217], v140 offset:41536
	s_waitcnt lgkmcnt(4)
	v_mfma_f32_32x32x16_bf16 v[50:65], v[218:221], v[222:225], v[50:65]
	v_mfma_f32_32x32x16_bf16 v[34:49], v[218:221], v[226:229], v[34:49]
	v_mfma_f32_32x32x16_bf16 v[18:33], v[230:233], v[222:225], v[18:33]
	v_mfma_f32_32x32x16_bf16 v[2:17], v[230:233], v[226:229], v[2:17]
	ds_read_b128 v[218:221], v140 offset:36960
	ds_read_b128 v[222:225], v141 offset:55392
	ds_read_b128 v[226:229], v141 offset:60000
	ds_read_b128 v[230:233], v140 offset:41568
	s_waitcnt lgkmcnt(4)
	v_mfma_f32_32x32x16_bf16 v[50:65], v[198:201], v[202:205], v[50:65]
	v_mfma_f32_32x32x16_bf16 v[34:49], v[198:201], v[206:209], v[34:49]
	v_mfma_f32_32x32x16_bf16 v[18:33], v[214:217], v[202:205], v[18:33]
	v_mfma_f32_32x32x16_bf16 v[2:17], v[214:217], v[206:209], v[2:17]
	s_waitcnt lgkmcnt(0)
	v_mfma_f32_32x32x16_bf16 v[50:65], v[218:221], v[222:225], v[50:65]
	v_mfma_f32_32x32x16_bf16 v[34:49], v[218:221], v[226:229], v[34:49]
	v_mfma_f32_32x32x16_bf16 v[18:33], v[230:233], v[222:225], v[18:33]
	v_mfma_f32_32x32x16_bf16 v[2:17], v[230:233], v[226:229], v[2:17]
	s_setprio 0
	s_waitcnt vmcnt(8)
	ds_write_b128 v188, v[98:101]
	ds_write_b128 v188, v[102:105] offset:4608
	ds_write_b128 v188, v[106:109] offset:9216
	ds_write_b128 v188, v[110:113] offset:13824
	ds_write_b128 v188, v[114:117] offset:18432
	ds_write_b128 v188, v[118:121] offset:23040
	ds_write_b128 v188, v[122:125] offset:27648
	ds_write_b128 v188, v[126:129] offset:32256
	s_waitcnt lgkmcnt(0)
	s_barrier
	ds_read_b128 v[198:201], v140
	ds_read_b128 v[202:205], v141 offset:18432
	ds_read_b128 v[206:209], v141 offset:23040
	ds_read_b128 v[214:217], v140 offset:4608
	ds_read_b128 v[218:221], v140 offset:32
	ds_read_b128 v[222:225], v141 offset:18464
	ds_read_b128 v[226:229], v141 offset:23072
	ds_read_b128 v[230:233], v140 offset:4640
	s_setprio 1
	s_waitcnt lgkmcnt(4)
	v_mfma_f32_32x32x16_bf16 v[50:65], v[198:201], v[202:205], v[50:65]
	v_mfma_f32_32x32x16_bf16 v[34:49], v[198:201], v[206:209], v[34:49]
	v_mfma_f32_32x32x16_bf16 v[18:33], v[214:217], v[202:205], v[18:33]
	v_mfma_f32_32x32x16_bf16 v[2:17], v[214:217], v[206:209], v[2:17]
	global_load_dwordx4 v[98:101], v[160:161], off offset:512
	global_load_dwordx4 v[102:105], v[162:163], off offset:512
	global_load_dwordx4 v[106:109], v[164:165], off offset:512
	global_load_dwordx4 v[110:113], v[166:167], off offset:512
	global_load_dwordx4 v[114:117], v[158:159], off offset:512
	global_load_dwordx4 v[118:121], v[168:169], off offset:512
	global_load_dwordx4 v[122:125], v[170:171], off offset:512
	global_load_dwordx4 v[126:129], v[172:173], off offset:512
	ds_read_b128 v[198:201], v140 offset:64
	ds_read_b128 v[202:205], v141 offset:18496
	ds_read_b128 v[206:209], v141 offset:23104
	ds_read_b128 v[214:217], v140 offset:4672
	s_waitcnt lgkmcnt(4)
	v_mfma_f32_32x32x16_bf16 v[50:65], v[218:221], v[222:225], v[50:65]
	v_mfma_f32_32x32x16_bf16 v[34:49], v[218:221], v[226:229], v[34:49]
	v_mfma_f32_32x32x16_bf16 v[18:33], v[230:233], v[222:225], v[18:33]
	v_mfma_f32_32x32x16_bf16 v[2:17], v[230:233], v[226:229], v[2:17]
	ds_read_b128 v[218:221], v140 offset:96
	ds_read_b128 v[222:225], v141 offset:18528
	ds_read_b128 v[226:229], v141 offset:23136
	ds_read_b128 v[230:233], v140 offset:4704
	s_waitcnt lgkmcnt(4)
	v_mfma_f32_32x32x16_bf16 v[50:65], v[198:201], v[202:205], v[50:65]
	v_mfma_f32_32x32x16_bf16 v[34:49], v[198:201], v[206:209], v[34:49]
	v_mfma_f32_32x32x16_bf16 v[18:33], v[214:217], v[202:205], v[18:33]
	v_mfma_f32_32x32x16_bf16 v[2:17], v[214:217], v[206:209], v[2:17]
	s_waitcnt lgkmcnt(0)
	v_mfma_f32_32x32x16_bf16 v[50:65], v[218:221], v[222:225], v[50:65]
	v_mfma_f32_32x32x16_bf16 v[34:49], v[218:221], v[226:229], v[34:49]
	v_mfma_f32_32x32x16_bf16 v[18:33], v[230:233], v[222:225], v[18:33]
	v_mfma_f32_32x32x16_bf16 v[2:17], v[230:233], v[226:229], v[2:17]
	s_setprio 0
	s_waitcnt vmcnt(8)
	ds_write_b128 v188, v[66:69] offset:36864
	ds_write_b128 v188, v[70:73] offset:41472
	ds_write_b128 v188, v[74:77] offset:46080
	ds_write_b128 v188, v[78:81] offset:50688
	ds_write_b128 v188, v[82:85] offset:55296
	ds_write_b128 v188, v[86:89] offset:59904
	ds_write_b128 v188, v[90:93] offset:64512
	ds_write_b128 v189, v[94:97] offset:13824
	s_waitcnt lgkmcnt(0)
	s_barrier
; __device__ __forceinline__ void gemm_kstep(const u16* sb, int wn, int wt, int r, int h, f32x16 (&acc)[2][2]) {
;   const u16* bw = sb + (wn * 64 + r) * LDT + h * 8;
;   const u16* bx = sb + TILE_U16 + (wt * 64 + r) * LDT + h * 8;
;   __builtin_amdgcn_s_setprio(1);
; #pragma unroll
;   for (int ks = 0; ks < 4; ++ks) {
;     bf16x8 a0 = *(const bf16x8*)(bw + ks * 16);
;     bf16x8 a1 = *(const bf16x8*)(bw + 32 * LDT + ks * 16);
;     bf16x8 b0 = *(const bf16x8*)(bx + ks * 16);
;     bf16x8 b1 = *(const bf16x8*)(bx + 32 * LDT + ks * 16);
;     acc[0][0] = mfma32(a0, b0, acc[0][0]);
;     acc[0][1] = mfma32(a0, b1, acc[0][1]);
;     acc[1][0] = mfma32(a1, b0, acc[1][0]);
;     acc[1][1] = mfma32(a1, b1, acc[1][1]);
;   }
;   __builtin_amdgcn_s_setprio(0);
; }
; __device__ void gemm_phase(const u16* __restrict__ Wb, int ldw, const u16* __restrict__ Xb, int ldx, int K,
;                            u16* __restrict__ outb, int ldo, int ntn, int ntiles, u16* lds) {
;     ...
;     for (int kt = 0; kt < nk; kt += 2) {
;       if (kt + 2 < nk) gs_load(B, gw, ldw, gx, ldx, (kt + 2) * 64);
;       else if (has_next) gs_load(B, gwn, ldw, gxn, ldx, 0);
;       gemm_kstep(lds, wn, wt, r, h, acc);
;       gs_store(A, lds + 2 * TILE_U16, lo);
;       __syncthreads();
;       if (kt + 3 < nk) gs_load(A, gw, ldw, gx, ldx, (kt + 3) * 64);
;       else if (has_next) gs_load(A, gwn, ldw, gxn, ldx, 64);
;       gemm_kstep(lds + 2 * TILE_U16, wn, wt, r, h, acc);
;       if (kt + 2 < nk) gs_store(B, lds, lo);
;       __syncthreads();
;     }
	ds_read_b128 v[198:201], v140 offset:36864
	ds_read_b128 v[202:205], v141 offset:55296
	ds_read_b128 v[206:209], v141 offset:59904
	ds_read_b128 v[214:217], v140 offset:41472
	ds_read_b128 v[218:221], v140 offset:36896
	ds_read_b128 v[222:225], v141 offset:55328
	ds_read_b128 v[226:229], v141 offset:59936
	ds_read_b128 v[230:233], v140 offset:41504
	s_setprio 1
	s_waitcnt lgkmcnt(4)
	v_mfma_f32_32x32x16_bf16 v[50:65], v[198:201], v[202:205], v[50:65]
	v_mfma_f32_32x32x16_bf16 v[34:49], v[198:201], v[206:209], v[34:49]
	v_mfma_f32_32x32x16_bf16 v[18:33], v[214:217], v[202:205], v[18:33]
	v_mfma_f32_32x32x16_bf16 v[2:17], v[214:217], v[206:209], v[2:17]
	global_load_dwordx4 v[66:69], v[160:161], off offset:640
	global_load_dwordx4 v[70:73], v[162:163], off offset:640
	global_load_dwordx4 v[74:77], v[164:165], off offset:640
	global_load_dwordx4 v[78:81], v[166:167], off offset:640
	global_load_dwordx4 v[82:85], v[158:159], off offset:640
	global_load_dwordx4 v[86:89], v[168:169], off offset:640
	global_load_dwordx4 v[90:93], v[170:171], off offset:640
	global_load_dwordx4 v[94:97], v[172:173], off offset:640
	ds_read_b128 v[198:201], v140 offset:36928
	ds_read_b128 v[202:205], v141 offset:55360
	ds_read_b128 v[206:209], v141 offset:59968
	ds_read_b128 v[214:217], v140 offset:41536
	s_waitcnt lgkmcnt(4)
	v_mfma_f32_32x32x16_bf16 v[50:65], v[218:221], v[222:225], v[50:65]
	v_mfma_f32_32x32x16_bf16 v[34:49], v[218:221], v[226:229], v[34:49]
	v_mfma_f32_32x32x16_bf16 v[18:33], v[230:233], v[222:225], v[18:33]
	v_mfma_f32_32x32x16_bf16 v[2:17], v[230:233], v[226:229], v[2:17]
	ds_read_b128 v[218:221], v140 offset:36960
	ds_read_b128 v[222:225], v141 offset:55392
	ds_read_b128 v[226:229], v141 offset:60000
	ds_read_b128 v[230:233], v140 offset:41568
	s_waitcnt lgkmcnt(4)
	v_mfma_f32_32x32x16_bf16 v[50:65], v[198:201], v[202:205], v[50:65]
	v_mfma_f32_32x32x16_bf16 v[34:49], v[198:201], v[206:209], v[34:49]
	v_mfma_f32_32x32x16_bf16 v[18:33], v[214:217], v[202:205], v[18:33]
	v_mfma_f32_32x32x16_bf16 v[2:17], v[214:217], v[206:209], v[2:17]
	s_waitcnt lgkmcnt(0)
	v_mfma_f32_32x32x16_bf16 v[50:65], v[218:221], v[222:225], v[50:65]
	v_mfma_f32_32x32x16_bf16 v[34:49], v[218:221], v[226:229], v[34:49]
	v_mfma_f32_32x32x16_bf16 v[18:33], v[230:233], v[222:225], v[18:33]
	v_mfma_f32_32x32x16_bf16 v[2:17], v[230:233], v[226:229], v[2:17]
	s_setprio 0
	s_waitcnt vmcnt(8)
	ds_write_b128 v188, v[98:101]
	ds_write_b128 v188, v[102:105] offset:4608
	ds_write_b128 v188, v[106:109] offset:9216
	ds_write_b128 v188, v[110:113] offset:13824
	ds_write_b128 v188, v[114:117] offset:18432
	ds_write_b128 v188, v[118:121] offset:23040
	ds_write_b128 v188, v[122:125] offset:27648
	ds_write_b128 v188, v[126:129] offset:32256
	s_waitcnt lgkmcnt(0)
	s_barrier
	ds_read_b128 v[198:201], v140
	ds_read_b128 v[202:205], v141 offset:18432
	ds_read_b128 v[206:209], v141 offset:23040
	ds_read_b128 v[214:217], v140 offset:4608
	ds_read_b128 v[218:221], v140 offset:32
	ds_read_b128 v[222:225], v141 offset:18464
	ds_read_b128 v[226:229], v141 offset:23072
	ds_read_b128 v[230:233], v140 offset:4640
	s_setprio 1
	s_waitcnt lgkmcnt(4)
	v_mfma_f32_32x32x16_bf16 v[50:65], v[198:201], v[202:205], v[50:65]
	v_mfma_f32_32x32x16_bf16 v[34:49], v[198:201], v[206:209], v[34:49]
	v_mfma_f32_32x32x16_bf16 v[18:33], v[214:217], v[202:205], v[18:33]
	v_mfma_f32_32x32x16_bf16 v[2:17], v[214:217], v[206:209], v[2:17]
	global_load_dwordx4 v[98:101], v[160:161], off offset:768
	global_load_dwordx4 v[102:105], v[162:163], off offset:768
	global_load_dwordx4 v[106:109], v[164:165], off offset:768
	global_load_dwordx4 v[110:113], v[166:167], off offset:768
	global_load_dwordx4 v[114:117], v[158:159], off offset:768
	global_load_dwordx4 v[118:121], v[168:169], off offset:768
	global_load_dwordx4 v[122:125], v[170:171], off offset:768
	global_load_dwordx4 v[126:129], v[172:173], off offset:768
	ds_read_b128 v[198:201], v140 offset:64
	ds_read_b128 v[202:205], v141 offset:18496
	ds_read_b128 v[206:209], v141 offset:23104
	ds_read_b128 v[214:217], v140 offset:4672
	s_waitcnt lgkmcnt(4)
	v_mfma_f32_32x32x16_bf16 v[50:65], v[218:221], v[222:225], v[50:65]
	v_mfma_f32_32x32x16_bf16 v[34:49], v[218:221], v[226:229], v[34:49]
	v_mfma_f32_32x32x16_bf16 v[18:33], v[230:233], v[222:225], v[18:33]
	v_mfma_f32_32x32x16_bf16 v[2:17], v[230:233], v[226:229], v[2:17]
	ds_read_b128 v[218:221], v140 offset:96
	ds_read_b128 v[222:225], v141 offset:18528
	ds_read_b128 v[226:229], v141 offset:23136
	ds_read_b128 v[230:233], v140 offset:4704
	s_waitcnt lgkmcnt(4)
	v_mfma_f32_32x32x16_bf16 v[50:65], v[198:201], v[202:205], v[50:65]
	v_mfma_f32_32x32x16_bf16 v[34:49], v[198:201], v[206:209], v[34:49]
	v_mfma_f32_32x32x16_bf16 v[18:33], v[214:217], v[202:205], v[18:33]
	v_mfma_f32_32x32x16_bf16 v[2:17], v[214:217], v[206:209], v[2:17]
	s_waitcnt lgkmcnt(0)
	v_mfma_f32_32x32x16_bf16 v[50:65], v[218:221], v[222:225], v[50:65]
	v_mfma_f32_32x32x16_bf16 v[34:49], v[218:221], v[226:229], v[34:49]
	v_mfma_f32_32x32x16_bf16 v[18:33], v[230:233], v[222:225], v[18:33]
	v_mfma_f32_32x32x16_bf16 v[2:17], v[230:233], v[226:229], v[2:17]
	s_setprio 0
	s_waitcnt vmcnt(8)
	ds_write_b128 v188, v[66:69] offset:36864
	ds_write_b128 v188, v[70:73] offset:41472
	ds_write_b128 v188, v[74:77] offset:46080
	ds_write_b128 v188, v[78:81] offset:50688
	ds_write_b128 v188, v[82:85] offset:55296
	ds_write_b128 v188, v[86:89] offset:59904
	ds_write_b128 v188, v[90:93] offset:64512
	ds_write_b128 v189, v[94:97] offset:13824
	s_waitcnt lgkmcnt(0)
	s_barrier
; __device__ __forceinline__ void gemm_kstep(const u16* sb, int wn, int wt, int r, int h, f32x16 (&acc)[2][2]) {
;   const u16* bw = sb + (wn * 64 + r) * LDT + h * 8;
;   const u16* bx = sb + TILE_U16 + (wt * 64 + r) * LDT + h * 8;
;   __builtin_amdgcn_s_setprio(1);
; #pragma unroll
;   for (int ks = 0; ks < 4; ++ks) {
;     bf16x8 a0 = *(const bf16x8*)(bw + ks * 16);
;     bf16x8 a1 = *(const bf16x8*)(bw + 32 * LDT + ks * 16);
;     bf16x8 b0 = *(const bf16x8*)(bx + ks * 16);
;     bf16x8 b1 = *(const bf16x8*)(bx + 32 * LDT + ks * 16);
;     acc[0][0] = mfma32(a0, b0, acc[0][0]);
;     acc[0][1] = mfma32(a0, b1, acc[0][1]);
;     acc[1][0] = mfma32(a1, b0, acc[1][0]);
;     acc[1][1] = mfma32(a1, b1, acc[1][1]);
;   }
;   __builtin_amdgcn_s_setprio(0);
; }
; __device__ void gemm_phase(const u16* __restrict__ Wb, int ldw, const u16* __restrict__ Xb, int ldx, int K,
;                            u16* __restrict__ outb, int ldo, int ntn, int ntiles, u16* lds) {
;     ...
;     for (int kt = 0; kt < nk; kt += 2) {
;       if (kt + 2 < nk) gs_load(B, gw, ldw, gx, ldx, (kt + 2) * 64);
;       else if (has_next) gs_load(B, gwn, ldw, gxn, ldx, 0);
;       gemm_kstep(lds, wn, wt, r, h, acc);
;       gs_store(A, lds + 2 * TILE_U16, lo);
;       __syncthreads();
;       if (kt + 3 < nk) gs_load(A, gw, ldw, gx, ldx, (kt + 3) * 64);
;       else if (has_next) gs_load(A, gwn, ldw, gxn, ldx, 64);
;       gemm_kstep(lds + 2 * TILE_U16, wn, wt, r, h, acc);
;       if (kt + 2 < nk) gs_store(B, lds, lo);
;       __syncthreads();
;     }
	ds_read_b128 v[198:201], v140 offset:36864
	ds_read_b128 v[202:205], v141 offset:55296
	ds_read_b128 v[206:209], v141 offset:59904
	ds_read_b128 v[214:217], v140 offset:41472
	ds_read_b128 v[218:221], v140 offset:36896
	ds_read_b128 v[222:225], v141 offset:55328
	ds_read_b128 v[226:229], v141 offset:59936
	ds_read_b128 v[230:233], v140 offset:41504
	s_setprio 1
	s_waitcnt lgkmcnt(4)
	v_mfma_f32_32x32x16_bf16 v[50:65], v[198:201], v[202:205], v[50:65]
	v_mfma_f32_32x32x16_bf16 v[34:49], v[198:201], v[206:209], v[34:49]
	v_mfma_f32_32x32x16_bf16 v[18:33], v[214:217], v[202:205], v[18:33]
	v_mfma_f32_32x32x16_bf16 v[2:17], v[214:217], v[206:209], v[2:17]
	global_load_dwordx4 v[66:69], v[160:161], off offset:896
	global_load_dwordx4 v[70:73], v[162:163], off offset:896
	global_load_dwordx4 v[74:77], v[164:165], off offset:896
	global_load_dwordx4 v[78:81], v[166:167], off offset:896
	global_load_dwordx4 v[82:85], v[158:159], off offset:896
	global_load_dwordx4 v[86:89], v[168:169], off offset:896
	global_load_dwordx4 v[90:93], v[170:171], off offset:896
	global_load_dwordx4 v[94:97], v[172:173], off offset:896
	ds_read_b128 v[198:201], v140 offset:36928
	ds_read_b128 v[202:205], v141 offset:55360
	ds_read_b128 v[206:209], v141 offset:59968
	ds_read_b128 v[214:217], v140 offset:41536
	s_waitcnt lgkmcnt(4)
	v_mfma_f32_32x32x16_bf16 v[50:65], v[218:221], v[222:225], v[50:65]
	v_mfma_f32_32x32x16_bf16 v[34:49], v[218:221], v[226:229], v[34:49]
	v_mfma_f32_32x32x16_bf16 v[18:33], v[230:233], v[222:225], v[18:33]
	v_mfma_f32_32x32x16_bf16 v[2:17], v[230:233], v[226:229], v[2:17]
	ds_read_b128 v[218:221], v140 offset:36960
	ds_read_b128 v[222:225], v141 offset:55392
	ds_read_b128 v[226:229], v141 offset:60000
	ds_read_b128 v[230:233], v140 offset:41568
	s_waitcnt lgkmcnt(4)
	v_mfma_f32_32x32x16_bf16 v[50:65], v[198:201], v[202:205], v[50:65]
	v_mfma_f32_32x32x16_bf16 v[34:49], v[198:201], v[206:209], v[34:49]
	v_mfma_f32_32x32x16_bf16 v[18:33], v[214:217], v[202:205], v[18:33]
	v_mfma_f32_32x32x16_bf16 v[2:17], v[214:217], v[206:209], v[2:17]
	s_waitcnt lgkmcnt(0)
	v_mfma_f32_32x32x16_bf16 v[50:65], v[218:221], v[222:225], v[50:65]
	v_mfma_f32_32x32x16_bf16 v[34:49], v[218:221], v[226:229], v[34:49]
	v_mfma_f32_32x32x16_bf16 v[18:33], v[230:233], v[222:225], v[18:33]
	v_mfma_f32_32x32x16_bf16 v[2:17], v[230:233], v[226:229], v[2:17]
	s_setprio 0
	s_waitcnt vmcnt(8)
	ds_write_b128 v188, v[98:101]
	ds_write_b128 v188, v[102:105] offset:4608
	ds_write_b128 v188, v[106:109] offset:9216
	ds_write_b128 v188, v[110:113] offset:13824
	ds_write_b128 v188, v[114:117] offset:18432
	ds_write_b128 v188, v[118:121] offset:23040
	ds_write_b128 v188, v[122:125] offset:27648
	ds_write_b128 v188, v[126:129] offset:32256
	s_waitcnt lgkmcnt(0)
	s_barrier
	ds_read_b128 v[198:201], v140
	ds_read_b128 v[202:205], v141 offset:18432
	ds_read_b128 v[206:209], v141 offset:23040
	ds_read_b128 v[214:217], v140 offset:4608
	ds_read_b128 v[218:221], v140 offset:32
	ds_read_b128 v[222:225], v141 offset:18464
	ds_read_b128 v[226:229], v141 offset:23072
	ds_read_b128 v[230:233], v140 offset:4640
	s_setprio 1
	s_waitcnt lgkmcnt(4)
	v_mfma_f32_32x32x16_bf16 v[50:65], v[198:201], v[202:205], v[50:65]
	v_mfma_f32_32x32x16_bf16 v[34:49], v[198:201], v[206:209], v[34:49]
	v_mfma_f32_32x32x16_bf16 v[18:33], v[214:217], v[202:205], v[18:33]
	v_mfma_f32_32x32x16_bf16 v[2:17], v[214:217], v[206:209], v[2:17]
	global_load_dwordx4 v[98:101], v[160:161], off offset:1024
	global_load_dwordx4 v[102:105], v[162:163], off offset:1024
	global_load_dwordx4 v[106:109], v[164:165], off offset:1024
	global_load_dwordx4 v[110:113], v[166:167], off offset:1024
	global_load_dwordx4 v[114:117], v[158:159], off offset:1024
	global_load_dwordx4 v[118:121], v[168:169], off offset:1024
	global_load_dwordx4 v[122:125], v[170:171], off offset:1024
	global_load_dwordx4 v[126:129], v[172:173], off offset:1024
	ds_read_b128 v[198:201], v140 offset:64
	ds_read_b128 v[202:205], v141 offset:18496
	ds_read_b128 v[206:209], v141 offset:23104
	ds_read_b128 v[214:217], v140 offset:4672
	s_waitcnt lgkmcnt(4)
	v_mfma_f32_32x32x16_bf16 v[50:65], v[218:221], v[222:225], v[50:65]
	v_mfma_f32_32x32x16_bf16 v[34:49], v[218:221], v[226:229], v[34:49]
	v_mfma_f32_32x32x16_bf16 v[18:33], v[230:233], v[222:225], v[18:33]
	v_mfma_f32_32x32x16_bf16 v[2:17], v[230:233], v[226:229], v[2:17]
	ds_read_b128 v[218:221], v140 offset:96
	ds_read_b128 v[222:225], v141 offset:18528
	ds_read_b128 v[226:229], v141 offset:23136
	ds_read_b128 v[230:233], v140 offset:4704
	s_waitcnt lgkmcnt(4)
	v_mfma_f32_32x32x16_bf16 v[50:65], v[198:201], v[202:205], v[50:65]
	v_mfma_f32_32x32x16_bf16 v[34:49], v[198:201], v[206:209], v[34:49]
	v_mfma_f32_32x32x16_bf16 v[18:33], v[214:217], v[202:205], v[18:33]
	v_mfma_f32_32x32x16_bf16 v[2:17], v[214:217], v[206:209], v[2:17]
	s_waitcnt lgkmcnt(0)
	v_mfma_f32_32x32x16_bf16 v[50:65], v[218:221], v[222:225], v[50:65]
	v_mfma_f32_32x32x16_bf16 v[34:49], v[218:221], v[226:229], v[34:49]
	v_mfma_f32_32x32x16_bf16 v[18:33], v[230:233], v[222:225], v[18:33]
	v_mfma_f32_32x32x16_bf16 v[2:17], v[230:233], v[226:229], v[2:17]
	s_setprio 0
	s_waitcnt vmcnt(8)
	ds_write_b128 v188, v[66:69] offset:36864
	ds_write_b128 v188, v[70:73] offset:41472
	ds_write_b128 v188, v[74:77] offset:46080
	ds_write_b128 v188, v[78:81] offset:50688
	ds_write_b128 v188, v[82:85] offset:55296
	ds_write_b128 v188, v[86:89] offset:59904
	ds_write_b128 v188, v[90:93] offset:64512
	ds_write_b128 v189, v[94:97] offset:13824
	s_waitcnt lgkmcnt(0)
	s_barrier
; __device__ __forceinline__ void gemm_kstep(const u16* sb, int wn, int wt, int r, int h, f32x16 (&acc)[2][2]) {
;   const u16* bw = sb + (wn * 64 + r) * LDT + h * 8;
;   const u16* bx = sb + TILE_U16 + (wt * 64 + r) * LDT + h * 8;
;   __builtin_amdgcn_s_setprio(1);
; #pragma unroll
;   for (int ks = 0; ks < 4; ++ks) {
;     bf16x8 a0 = *(const bf16x8*)(bw + ks * 16);
;     bf16x8 a1 = *(const bf16x8*)(bw + 32 * LDT + ks * 16);
;     bf16x8 b0 = *(const bf16x8*)(bx + ks * 16);
;     bf16x8 b1 = *(const bf16x8*)(bx + 32 * LDT + ks * 16);
;     acc[0][0] = mfma32(a0, b0, acc[0][0]);
;     acc[0][1] = mfma32(a0, b1, acc[0][1]);
;     acc[1][0] = mfma32(a1, b0, acc[1][0]);
;     acc[1][1] = mfma32(a1, b1, acc[1][1]);
;   }
;   __builtin_amdgcn_s_setprio(0);
; }
; __device__ void gemm_phase(const u16* __restrict__ Wb, int ldw, const u16* __restrict__ Xb, int ldx, int K,
;                            u16* __restrict__ outb, int ldo, int ntn, int ntiles, u16* lds) {
;     ...
;     for (int kt = 0; kt < nk; kt += 2) {
;       if (kt + 2 < nk) gs_load(B, gw, ldw, gx, ldx, (kt + 2) * 64);
;       else if (has_next) gs_load(B, gwn, ldw, gxn, ldx, 0);
;       gemm_kstep(lds, wn, wt, r, h, acc);
;       gs_store(A, lds + 2 * TILE_U16, lo);
;       __syncthreads();
;       if (kt + 3 < nk) gs_load(A, gw, ldw, gx, ldx, (kt + 3) * 64);
;       else if (has_next) gs_load(A, gwn, ldw, gxn, ldx, 64);
;       gemm_kstep(lds + 2 * TILE_U16, wn, wt, r, h, acc);
;       if (kt + 2 < nk) gs_store(B, lds, lo);
;       __syncthreads();
;     }
	ds_read_b128 v[198:201], v140 offset:36864
	ds_read_b128 v[202:205], v141 offset:55296
	ds_read_b128 v[206:209], v141 offset:59904
	ds_read_b128 v[214:217], v140 offset:41472
	ds_read_b128 v[218:221], v140 offset:36896
	ds_read_b128 v[222:225], v141 offset:55328
	ds_read_b128 v[226:229], v141 offset:59936
	ds_read_b128 v[230:233], v140 offset:41504
	s_setprio 1
	s_waitcnt lgkmcnt(4)
	v_mfma_f32_32x32x16_bf16 v[50:65], v[198:201], v[202:205], v[50:65]
	v_mfma_f32_32x32x16_bf16 v[34:49], v[198:201], v[206:209], v[34:49]
	v_mfma_f32_32x32x16_bf16 v[18:33], v[214:217], v[202:205], v[18:33]
	v_mfma_f32_32x32x16_bf16 v[2:17], v[214:217], v[206:209], v[2:17]
	global_load_dwordx4 v[66:69], v[160:161], off offset:1152
	global_load_dwordx4 v[70:73], v[162:163], off offset:1152
	global_load_dwordx4 v[74:77], v[164:165], off offset:1152
	global_load_dwordx4 v[78:81], v[166:167], off offset:1152
	global_load_dwordx4 v[82:85], v[158:159], off offset:1152
	global_load_dwordx4 v[86:89], v[168:169], off offset:1152
	global_load_dwordx4 v[90:93], v[170:171], off offset:1152
	global_load_dwordx4 v[94:97], v[172:173], off offset:1152
	ds_read_b128 v[198:201], v140 offset:36928
	ds_read_b128 v[202:205], v141 offset:55360
	ds_read_b128 v[206:209], v141 offset:59968
	ds_read_b128 v[214:217], v140 offset:41536
	s_waitcnt lgkmcnt(4)
	v_mfma_f32_32x32x16_bf16 v[50:65], v[218:221], v[222:225], v[50:65]
	v_mfma_f32_32x32x16_bf16 v[34:49], v[218:221], v[226:229], v[34:49]
	v_mfma_f32_32x32x16_bf16 v[18:33], v[230:233], v[222:225], v[18:33]
	v_mfma_f32_32x32x16_bf16 v[2:17], v[230:233], v[226:229], v[2:17]
	ds_read_b128 v[218:221], v140 offset:36960
	ds_read_b128 v[222:225], v141 offset:55392
	ds_read_b128 v[226:229], v141 offset:60000
	ds_read_b128 v[230:233], v140 offset:41568
	s_waitcnt lgkmcnt(4)
	v_mfma_f32_32x32x16_bf16 v[50:65], v[198:201], v[202:205], v[50:65]
	v_mfma_f32_32x32x16_bf16 v[34:49], v[198:201], v[206:209], v[34:49]
	v_mfma_f32_32x32x16_bf16 v[18:33], v[214:217], v[202:205], v[18:33]
	v_mfma_f32_32x32x16_bf16 v[2:17], v[214:217], v[206:209], v[2:17]
	s_waitcnt lgkmcnt(0)
	v_mfma_f32_32x32x16_bf16 v[50:65], v[218:221], v[222:225], v[50:65]
	v_mfma_f32_32x32x16_bf16 v[34:49], v[218:221], v[226:229], v[34:49]
	v_mfma_f32_32x32x16_bf16 v[18:33], v[230:233], v[222:225], v[18:33]
	v_mfma_f32_32x32x16_bf16 v[2:17], v[230:233], v[226:229], v[2:17]
	s_setprio 0
	s_waitcnt vmcnt(8)
	ds_write_b128 v188, v[98:101]
	ds_write_b128 v188, v[102:105] offset:4608
	ds_write_b128 v188, v[106:109] offset:9216
	ds_write_b128 v188, v[110:113] offset:13824
	ds_write_b128 v188, v[114:117] offset:18432
	ds_write_b128 v188, v[118:121] offset:23040
	ds_write_b128 v188, v[122:125] offset:27648
	ds_write_b128 v188, v[126:129] offset:32256
	s_waitcnt lgkmcnt(0)
	s_barrier
	ds_read_b128 v[198:201], v140
	ds_read_b128 v[202:205], v141 offset:18432
	ds_read_b128 v[206:209], v141 offset:23040
	ds_read_b128 v[214:217], v140 offset:4608
	ds_read_b128 v[218:221], v140 offset:32
	ds_read_b128 v[222:225], v141 offset:18464
	ds_read_b128 v[226:229], v141 offset:23072
	ds_read_b128 v[230:233], v140 offset:4640
	s_setprio 1
	s_waitcnt lgkmcnt(4)
	v_mfma_f32_32x32x16_bf16 v[50:65], v[198:201], v[202:205], v[50:65]
	v_mfma_f32_32x32x16_bf16 v[34:49], v[198:201], v[206:209], v[34:49]
	v_mfma_f32_32x32x16_bf16 v[18:33], v[214:217], v[202:205], v[18:33]
	v_mfma_f32_32x32x16_bf16 v[2:17], v[214:217], v[206:209], v[2:17]
	global_load_dwordx4 v[98:101], v[160:161], off offset:1280
	global_load_dwordx4 v[102:105], v[162:163], off offset:1280
	global_load_dwordx4 v[106:109], v[164:165], off offset:1280
	global_load_dwordx4 v[110:113], v[166:167], off offset:1280
	global_load_dwordx4 v[114:117], v[158:159], off offset:1280
	global_load_dwordx4 v[118:121], v[168:169], off offset:1280
	global_load_dwordx4 v[122:125], v[170:171], off offset:1280
	global_load_dwordx4 v[126:129], v[172:173], off offset:1280
	ds_read_b128 v[198:201], v140 offset:64
	ds_read_b128 v[202:205], v141 offset:18496
	ds_read_b128 v[206:209], v141 offset:23104
	ds_read_b128 v[214:217], v140 offset:4672
	s_waitcnt lgkmcnt(4)
	v_mfma_f32_32x32x16_bf16 v[50:65], v[218:221], v[222:225], v[50:65]
	v_mfma_f32_32x32x16_bf16 v[34:49], v[218:221], v[226:229], v[34:49]
	v_mfma_f32_32x32x16_bf16 v[18:33], v[230:233], v[222:225], v[18:33]
	v_mfma_f32_32x32x16_bf16 v[2:17], v[230:233], v[226:229], v[2:17]
	ds_read_b128 v[218:221], v140 offset:96
	ds_read_b128 v[222:225], v141 offset:18528
	ds_read_b128 v[226:229], v141 offset:23136
	ds_read_b128 v[230:233], v140 offset:4704
	s_waitcnt lgkmcnt(4)
	v_mfma_f32_32x32x16_bf16 v[50:65], v[198:201], v[202:205], v[50:65]
	v_mfma_f32_32x32x16_bf16 v[34:49], v[198:201], v[206:209], v[34:49]
	v_mfma_f32_32x32x16_bf16 v[18:33], v[214:217], v[202:205], v[18:33]
	v_mfma_f32_32x32x16_bf16 v[2:17], v[214:217], v[206:209], v[2:17]
	s_waitcnt lgkmcnt(0)
	v_mfma_f32_32x32x16_bf16 v[50:65], v[218:221], v[222:225], v[50:65]
	v_mfma_f32_32x32x16_bf16 v[34:49], v[218:221], v[226:229], v[34:49]
	v_mfma_f32_32x32x16_bf16 v[18:33], v[230:233], v[222:225], v[18:33]
	v_mfma_f32_32x32x16_bf16 v[2:17], v[230:233], v[226:229], v[2:17]
	s_setprio 0
	s_waitcnt vmcnt(8)
	ds_write_b128 v188, v[66:69] offset:36864
	ds_write_b128 v188, v[70:73] offset:41472
	ds_write_b128 v188, v[74:77] offset:46080
	ds_write_b128 v188, v[78:81] offset:50688
	ds_write_b128 v188, v[82:85] offset:55296
	ds_write_b128 v188, v[86:89] offset:59904
	ds_write_b128 v188, v[90:93] offset:64512
	ds_write_b128 v189, v[94:97] offset:13824
	s_waitcnt lgkmcnt(0)
	s_barrier
; __device__ __forceinline__ void gemm_kstep(const u16* sb, int wn, int wt, int r, int h, f32x16 (&acc)[2][2]) {
;   const u16* bw = sb + (wn * 64 + r) * LDT + h * 8;
;   const u16* bx = sb + TILE_U16 + (wt * 64 + r) * LDT + h * 8;
;   __builtin_amdgcn_s_setprio(1);
; #pragma unroll
;   for (int ks = 0; ks < 4; ++ks) {
;     bf16x8 a0 = *(const bf16x8*)(bw + ks * 16);
;     bf16x8 a1 = *(const bf16x8*)(bw + 32 * LDT + ks * 16);
;     bf16x8 b0 = *(const bf16x8*)(bx + ks * 16);
;     bf16x8 b1 = *(const bf16x8*)(bx + 32 * LDT + ks * 16);
;     acc[0][0] = mfma32(a0, b0, acc[0][0]);
;     acc[0][1] = mfma32(a0, b1, acc[0][1]);
;     acc[1][0] = mfma32(a1, b0, acc[1][0]);
;     acc[1][1] = mfma32(a1, b1, acc[1][1]);
;   }
;   __builtin_amdgcn_s_setprio(0);
; }
; __device__ void gemm_phase(const u16* __restrict__ Wb, int ldw, const u16* __restrict__ Xb, int ldx, int K,
;                            u16* __restrict__ outb, int ldo, int ntn, int ntiles, u16* lds) {
;     ...
;     for (int kt = 0; kt < nk; kt += 2) {
;       if (kt + 2 < nk) gs_load(B, gw, ldw, gx, ldx, (kt + 2) * 64);
;       else if (has_next) gs_load(B, gwn, ldw, gxn, ldx, 0);
;       gemm_kstep(lds, wn, wt, r, h, acc);
;       gs_store(A, lds + 2 * TILE_U16, lo);
;       __syncthreads();
;       if (kt + 3 < nk) gs_load(A, gw, ldw, gx, ldx, (kt + 3) * 64);
;       else if (has_next) gs_load(A, gwn, ldw, gxn, ldx, 64);
;       gemm_kstep(lds + 2 * TILE_U16, wn, wt, r, h, acc);
;       if (kt + 2 < nk) gs_store(B, lds, lo);
;       __syncthreads();
;     }
	ds_read_b128 v[198:201], v140 offset:36864
	ds_read_b128 v[202:205], v141 offset:55296
	ds_read_b128 v[206:209], v141 offset:59904
	ds_read_b128 v[214:217], v140 offset:41472
	ds_read_b128 v[218:221], v140 offset:36896
	ds_read_b128 v[222:225], v141 offset:55328
	ds_read_b128 v[226:229], v141 offset:59936
	ds_read_b128 v[230:233], v140 offset:41504
	s_setprio 1
	s_waitcnt lgkmcnt(4)
	v_mfma_f32_32x32x16_bf16 v[50:65], v[198:201], v[202:205], v[50:65]
	v_mfma_f32_32x32x16_bf16 v[34:49], v[198:201], v[206:209], v[34:49]
	v_mfma_f32_32x32x16_bf16 v[18:33], v[214:217], v[202:205], v[18:33]
	v_mfma_f32_32x32x16_bf16 v[2:17], v[214:217], v[206:209], v[2:17]
	global_load_dwordx4 v[66:69], v[160:161], off offset:1408
	global_load_dwordx4 v[70:73], v[162:163], off offset:1408
	global_load_dwordx4 v[74:77], v[164:165], off offset:1408
	global_load_dwordx4 v[78:81], v[166:167], off offset:1408
	global_load_dwordx4 v[82:85], v[158:159], off offset:1408
	global_load_dwordx4 v[86:89], v[168:169], off offset:1408
	global_load_dwordx4 v[90:93], v[170:171], off offset:1408
	global_load_dwordx4 v[94:97], v[172:173], off offset:1408
	ds_read_b128 v[198:201], v140 offset:36928
	ds_read_b128 v[202:205], v141 offset:55360
	ds_read_b128 v[206:209], v141 offset:59968
	ds_read_b128 v[214:217], v140 offset:41536
	s_waitcnt lgkmcnt(4)
	v_mfma_f32_32x32x16_bf16 v[50:65], v[218:221], v[222:225], v[50:65]
	v_mfma_f32_32x32x16_bf16 v[34:49], v[218:221], v[226:229], v[34:49]
	v_mfma_f32_32x32x16_bf16 v[18:33], v[230:233], v[222:225], v[18:33]
	v_mfma_f32_32x32x16_bf16 v[2:17], v[230:233], v[226:229], v[2:17]
	ds_read_b128 v[218:221], v140 offset:36960
	ds_read_b128 v[222:225], v141 offset:55392
	ds_read_b128 v[226:229], v141 offset:60000
	ds_read_b128 v[230:233], v140 offset:41568
	s_waitcnt lgkmcnt(4)
	v_mfma_f32_32x32x16_bf16 v[50:65], v[198:201], v[202:205], v[50:65]
	v_mfma_f32_32x32x16_bf16 v[34:49], v[198:201], v[206:209], v[34:49]
	v_mfma_f32_32x32x16_bf16 v[18:33], v[214:217], v[202:205], v[18:33]
	v_mfma_f32_32x32x16_bf16 v[2:17], v[214:217], v[206:209], v[2:17]
	s_waitcnt lgkmcnt(0)
	v_mfma_f32_32x32x16_bf16 v[50:65], v[218:221], v[222:225], v[50:65]
	v_mfma_f32_32x32x16_bf16 v[34:49], v[218:221], v[226:229], v[34:49]
	v_mfma_f32_32x32x16_bf16 v[18:33], v[230:233], v[222:225], v[18:33]
	v_mfma_f32_32x32x16_bf16 v[2:17], v[230:233], v[226:229], v[2:17]
	s_setprio 0
	s_waitcnt vmcnt(8)
	ds_write_b128 v188, v[98:101]
	ds_write_b128 v188, v[102:105] offset:4608
	ds_write_b128 v188, v[106:109] offset:9216
	ds_write_b128 v188, v[110:113] offset:13824
	ds_write_b128 v188, v[114:117] offset:18432
	ds_write_b128 v188, v[118:121] offset:23040
	ds_write_b128 v188, v[122:125] offset:27648
	ds_write_b128 v188, v[126:129] offset:32256
	s_waitcnt lgkmcnt(0)
	s_barrier
	ds_read_b128 v[198:201], v140
	ds_read_b128 v[202:205], v141 offset:18432
	ds_read_b128 v[206:209], v141 offset:23040
	ds_read_b128 v[214:217], v140 offset:4608
	ds_read_b128 v[218:221], v140 offset:32
	ds_read_b128 v[222:225], v141 offset:18464
	ds_read_b128 v[226:229], v141 offset:23072
	ds_read_b128 v[230:233], v140 offset:4640
	s_setprio 1
	s_waitcnt lgkmcnt(4)
	v_mfma_f32_32x32x16_bf16 v[50:65], v[198:201], v[202:205], v[50:65]
	v_mfma_f32_32x32x16_bf16 v[34:49], v[198:201], v[206:209], v[34:49]
	v_mfma_f32_32x32x16_bf16 v[18:33], v[214:217], v[202:205], v[18:33]
	v_mfma_f32_32x32x16_bf16 v[2:17], v[214:217], v[206:209], v[2:17]
	global_load_dwordx4 v[98:101], v[160:161], off offset:1536
	global_load_dwordx4 v[102:105], v[162:163], off offset:1536
	global_load_dwordx4 v[106:109], v[164:165], off offset:1536
	global_load_dwordx4 v[110:113], v[166:167], off offset:1536
	global_load_dwordx4 v[114:117], v[158:159], off offset:1536
	global_load_dwordx4 v[118:121], v[168:169], off offset:1536
	global_load_dwordx4 v[122:125], v[170:171], off offset:1536
	global_load_dwordx4 v[126:129], v[172:173], off offset:1536
	ds_read_b128 v[198:201], v140 offset:64
	ds_read_b128 v[202:205], v141 offset:18496
	ds_read_b128 v[206:209], v141 offset:23104
	ds_read_b128 v[214:217], v140 offset:4672
	s_waitcnt lgkmcnt(4)
	v_mfma_f32_32x32x16_bf16 v[50:65], v[218:221], v[222:225], v[50:65]
	v_mfma_f32_32x32x16_bf16 v[34:49], v[218:221], v[226:229], v[34:49]
	v_mfma_f32_32x32x16_bf16 v[18:33], v[230:233], v[222:225], v[18:33]
	v_mfma_f32_32x32x16_bf16 v[2:17], v[230:233], v[226:229], v[2:17]
	ds_read_b128 v[218:221], v140 offset:96
	ds_read_b128 v[222:225], v141 offset:18528
	ds_read_b128 v[226:229], v141 offset:23136
	ds_read_b128 v[230:233], v140 offset:4704
	s_waitcnt lgkmcnt(4)
	v_mfma_f32_32x32x16_bf16 v[50:65], v[198:201], v[202:205], v[50:65]
	v_mfma_f32_32x32x16_bf16 v[34:49], v[198:201], v[206:209], v[34:49]
	v_mfma_f32_32x32x16_bf16 v[18:33], v[214:217], v[202:205], v[18:33]
	v_mfma_f32_32x32x16_bf16 v[2:17], v[214:217], v[206:209], v[2:17]
	s_waitcnt lgkmcnt(0)
	v_mfma_f32_32x32x16_bf16 v[50:65], v[218:221], v[222:225], v[50:65]
	v_mfma_f32_32x32x16_bf16 v[34:49], v[218:221], v[226:229], v[34:49]
	v_mfma_f32_32x32x16_bf16 v[18:33], v[230:233], v[222:225], v[18:33]
	v_mfma_f32_32x32x16_bf16 v[2:17], v[230:233], v[226:229], v[2:17]
	s_setprio 0
	s_waitcnt vmcnt(8)
	ds_write_b128 v188, v[66:69] offset:36864
	ds_write_b128 v188, v[70:73] offset:41472
	ds_write_b128 v188, v[74:77] offset:46080
	ds_write_b128 v188, v[78:81] offset:50688
	ds_write_b128 v188, v[82:85] offset:55296
	ds_write_b128 v188, v[86:89] offset:59904
	ds_write_b128 v188, v[90:93] offset:64512
	ds_write_b128 v189, v[94:97] offset:13824
	s_waitcnt lgkmcnt(0)
	s_barrier
; __device__ __forceinline__ void gemm_kstep(const u16* sb, int wn, int wt, int r, int h, f32x16 (&acc)[2][2]) {
;   const u16* bw = sb + (wn * 64 + r) * LDT + h * 8;
;   const u16* bx = sb + TILE_U16 + (wt * 64 + r) * LDT + h * 8;
;   __builtin_amdgcn_s_setprio(1);
; #pragma unroll
;   for (int ks = 0; ks < 4; ++ks) {
;     bf16x8 a0 = *(const bf16x8*)(bw + ks * 16);
;     bf16x8 a1 = *(const bf16x8*)(bw + 32 * LDT + ks * 16);
;     bf16x8 b0 = *(const bf16x8*)(bx + ks * 16);
;     bf16x8 b1 = *(const bf16x8*)(bx + 32 * LDT + ks * 16);
;     acc[0][0] = mfma32(a0, b0, acc[0][0]);
;     acc[0][1] = mfma32(a0, b1, acc[0][1]);
;     acc[1][0] = mfma32(a1, b0, acc[1][0]);
;     acc[1][1] = mfma32(a1, b1, acc[1][1]);
;   }
;   __builtin_amdgcn_s_setprio(0);
; }
; __device__ void gemm_phase(const u16* __restrict__ Wb, int ldw, const u16* __restrict__ Xb, int ldx, int K,
;                            u16* __restrict__ outb, int ldo, int ntn, int ntiles, u16* lds) {
;     ...
;     for (int kt = 0; kt < nk; kt += 2) {
;       if (kt + 2 < nk) gs_load(B, gw, ldw, gx, ldx, (kt + 2) * 64);
;       else if (has_next) gs_load(B, gwn, ldw, gxn, ldx, 0);
;       gemm_kstep(lds, wn, wt, r, h, acc);
;       gs_store(A, lds + 2 * TILE_U16, lo);
;       __syncthreads();
;       if (kt + 3 < nk) gs_load(A, gw, ldw, gx, ldx, (kt + 3) * 64);
;       else if (has_next) gs_load(A, gwn, ldw, gxn, ldx, 64);
;       gemm_kstep(lds + 2 * TILE_U16, wn, wt, r, h, acc);
;       if (kt + 2 < nk) gs_store(B, lds, lo);
;       __syncthreads();
;     }
	ds_read_b128 v[198:201], v140 offset:36864
	ds_read_b128 v[202:205], v141 offset:55296
	ds_read_b128 v[206:209], v141 offset:59904
	ds_read_b128 v[214:217], v140 offset:41472
	ds_read_b128 v[218:221], v140 offset:36896
	ds_read_b128 v[222:225], v141 offset:55328
	ds_read_b128 v[226:229], v141 offset:59936
	ds_read_b128 v[230:233], v140 offset:41504
	s_setprio 1
	s_waitcnt lgkmcnt(4)
	v_mfma_f32_32x32x16_bf16 v[50:65], v[198:201], v[202:205], v[50:65]
	v_mfma_f32_32x32x16_bf16 v[34:49], v[198:201], v[206:209], v[34:49]
	v_mfma_f32_32x32x16_bf16 v[18:33], v[214:217], v[202:205], v[18:33]
	v_mfma_f32_32x32x16_bf16 v[2:17], v[214:217], v[206:209], v[2:17]
	global_load_dwordx4 v[66:69], v[160:161], off offset:1664
	global_load_dwordx4 v[70:73], v[162:163], off offset:1664
	global_load_dwordx4 v[74:77], v[164:165], off offset:1664
	global_load_dwordx4 v[78:81], v[166:167], off offset:1664
	global_load_dwordx4 v[82:85], v[158:159], off offset:1664
	global_load_dwordx4 v[86:89], v[168:169], off offset:1664
	global_load_dwordx4 v[90:93], v[170:171], off offset:1664
	global_load_dwordx4 v[94:97], v[172:173], off offset:1664
	ds_read_b128 v[198:201], v140 offset:36928
	ds_read_b128 v[202:205], v141 offset:55360
	ds_read_b128 v[206:209], v141 offset:59968
	ds_read_b128 v[214:217], v140 offset:41536
	s_waitcnt lgkmcnt(4)
	v_mfma_f32_32x32x16_bf16 v[50:65], v[218:221], v[222:225], v[50:65]
	v_mfma_f32_32x32x16_bf16 v[34:49], v[218:221], v[226:229], v[34:49]
	v_mfma_f32_32x32x16_bf16 v[18:33], v[230:233], v[222:225], v[18:33]
	v_mfma_f32_32x32x16_bf16 v[2:17], v[230:233], v[226:229], v[2:17]
	ds_read_b128 v[218:221], v140 offset:36960
	ds_read_b128 v[222:225], v141 offset:55392
	ds_read_b128 v[226:229], v141 offset:60000
	ds_read_b128 v[230:233], v140 offset:41568
	s_waitcnt lgkmcnt(4)
	v_mfma_f32_32x32x16_bf16 v[50:65], v[198:201], v[202:205], v[50:65]
	v_mfma_f32_32x32x16_bf16 v[34:49], v[198:201], v[206:209], v[34:49]
	v_mfma_f32_32x32x16_bf16 v[18:33], v[214:217], v[202:205], v[18:33]
	v_mfma_f32_32x32x16_bf16 v[2:17], v[214:217], v[206:209], v[2:17]
	s_waitcnt lgkmcnt(0)
	v_mfma_f32_32x32x16_bf16 v[50:65], v[218:221], v[222:225], v[50:65]
	v_mfma_f32_32x32x16_bf16 v[34:49], v[218:221], v[226:229], v[34:49]
	v_mfma_f32_32x32x16_bf16 v[18:33], v[230:233], v[222:225], v[18:33]
	v_mfma_f32_32x32x16_bf16 v[2:17], v[230:233], v[226:229], v[2:17]
	s_setprio 0
	s_waitcnt vmcnt(8)
	ds_write_b128 v188, v[98:101]
	ds_write_b128 v188, v[102:105] offset:4608
	ds_write_b128 v188, v[106:109] offset:9216
	ds_write_b128 v188, v[110:113] offset:13824
	ds_write_b128 v188, v[114:117] offset:18432
	ds_write_b128 v188, v[118:121] offset:23040
	ds_write_b128 v188, v[122:125] offset:27648
	ds_write_b128 v188, v[126:129] offset:32256
	s_waitcnt lgkmcnt(0)
	s_barrier
	ds_read_b128 v[198:201], v140
	ds_read_b128 v[202:205], v141 offset:18432
	ds_read_b128 v[206:209], v141 offset:23040
	ds_read_b128 v[214:217], v140 offset:4608
	ds_read_b128 v[218:221], v140 offset:32
	ds_read_b128 v[222:225], v141 offset:18464
	ds_read_b128 v[226:229], v141 offset:23072
	ds_read_b128 v[230:233], v140 offset:4640
	s_setprio 1
	s_waitcnt lgkmcnt(4)
	v_mfma_f32_32x32x16_bf16 v[50:65], v[198:201], v[202:205], v[50:65]
	v_mfma_f32_32x32x16_bf16 v[34:49], v[198:201], v[206:209], v[34:49]
	v_mfma_f32_32x32x16_bf16 v[18:33], v[214:217], v[202:205], v[18:33]
	v_mfma_f32_32x32x16_bf16 v[2:17], v[214:217], v[206:209], v[2:17]
	global_load_dwordx4 v[98:101], v[160:161], off offset:1792
	global_load_dwordx4 v[102:105], v[162:163], off offset:1792
	global_load_dwordx4 v[106:109], v[164:165], off offset:1792
	global_load_dwordx4 v[110:113], v[166:167], off offset:1792
	global_load_dwordx4 v[114:117], v[158:159], off offset:1792
	global_load_dwordx4 v[118:121], v[168:169], off offset:1792
	global_load_dwordx4 v[122:125], v[170:171], off offset:1792
	global_load_dwordx4 v[126:129], v[172:173], off offset:1792
	ds_read_b128 v[198:201], v140 offset:64
	ds_read_b128 v[202:205], v141 offset:18496
	ds_read_b128 v[206:209], v141 offset:23104
	ds_read_b128 v[214:217], v140 offset:4672
	s_waitcnt lgkmcnt(4)
	v_mfma_f32_32x32x16_bf16 v[50:65], v[218:221], v[222:225], v[50:65]
	v_mfma_f32_32x32x16_bf16 v[34:49], v[218:221], v[226:229], v[34:49]
	v_mfma_f32_32x32x16_bf16 v[18:33], v[230:233], v[222:225], v[18:33]
	v_mfma_f32_32x32x16_bf16 v[2:17], v[230:233], v[226:229], v[2:17]
	ds_read_b128 v[218:221], v140 offset:96
	ds_read_b128 v[222:225], v141 offset:18528
	ds_read_b128 v[226:229], v141 offset:23136
	ds_read_b128 v[230:233], v140 offset:4704
	s_waitcnt lgkmcnt(4)
	v_mfma_f32_32x32x16_bf16 v[50:65], v[198:201], v[202:205], v[50:65]
	v_mfma_f32_32x32x16_bf16 v[34:49], v[198:201], v[206:209], v[34:49]
	v_mfma_f32_32x32x16_bf16 v[18:33], v[214:217], v[202:205], v[18:33]
	v_mfma_f32_32x32x16_bf16 v[2:17], v[214:217], v[206:209], v[2:17]
	s_waitcnt lgkmcnt(0)
	v_mfma_f32_32x32x16_bf16 v[50:65], v[218:221], v[222:225], v[50:65]
	v_mfma_f32_32x32x16_bf16 v[34:49], v[218:221], v[226:229], v[34:49]
	v_mfma_f32_32x32x16_bf16 v[18:33], v[230:233], v[222:225], v[18:33]
	v_mfma_f32_32x32x16_bf16 v[2:17], v[230:233], v[226:229], v[2:17]
	s_setprio 0
	s_waitcnt vmcnt(8)
	ds_write_b128 v188, v[66:69] offset:36864
	ds_write_b128 v188, v[70:73] offset:41472
	ds_write_b128 v188, v[74:77] offset:46080
	ds_write_b128 v188, v[78:81] offset:50688
	ds_write_b128 v188, v[82:85] offset:55296
	ds_write_b128 v188, v[86:89] offset:59904
	ds_write_b128 v188, v[90:93] offset:64512
	ds_write_b128 v189, v[94:97] offset:13824
	s_waitcnt lgkmcnt(0)
	s_barrier
; __device__ __forceinline__ void gemm_kstep(const u16* sb, int wn, int wt, int r, int h, f32x16 (&acc)[2][2]) {
;   const u16* bw = sb + (wn * 64 + r) * LDT + h * 8;
;   const u16* bx = sb + TILE_U16 + (wt * 64 + r) * LDT + h * 8;
;   __builtin_amdgcn_s_setprio(1);
; #pragma unroll
;   for (int ks = 0; ks < 4; ++ks) {
;     bf16x8 a0 = *(const bf16x8*)(bw + ks * 16);
;     bf16x8 a1 = *(const bf16x8*)(bw + 32 * LDT + ks * 16);
;     bf16x8 b0 = *(const bf16x8*)(bx + ks * 16);
;     bf16x8 b1 = *(const bf16x8*)(bx + 32 * LDT + ks * 16);
;     acc[0][0] = mfma32(a0, b0, acc[0][0]);
;     acc[0][1] = mfma32(a0, b1, acc[0][1]);
;     acc[1][0] = mfma32(a1, b0, acc[1][0]);
;     acc[1][1] = mfma32(a1, b1, acc[1][1]);
;   }
;   __builtin_amdgcn_s_setprio(0);
; }
; __device__ void gemm_phase(const u16* __restrict__ Wb, int ldw, const u16* __restrict__ Xb, int ldx, int K,
;                            u16* __restrict__ outb, int ldo, int ntn, int ntiles, u16* lds) {
;     ...
;     for (int kt = 0; kt < nk; kt += 2) {
;       if (kt + 2 < nk) gs_load(B, gw, ldw, gx, ldx, (kt + 2) * 64);
;       else if (has_next) gs_load(B, gwn, ldw, gxn, ldx, 0);
	global_load_dwordx4 v[66:69], v[160:161], off offset:1920
	global_load_dwordx4 v[70:73], v[162:163], off offset:1920
	global_load_dwordx4 v[74:77], v[164:165], off offset:1920
	global_load_dwordx4 v[78:81], v[166:167], off offset:1920
	global_load_dwordx4 v[82:85], v[158:159], off offset:1920
	global_load_dwordx4 v[86:89], v[168:169], off offset:1920
	global_load_dwordx4 v[90:93], v[170:171], off offset:1920
	global_load_dwordx4 v[94:97], v[172:173], off offset:1920
	ds_read_b128 v[158:161], v140 offset:36864
	ds_read_b128 v[162:165], v141 offset:55296
	ds_read_b128 v[166:169], v141 offset:59904
	ds_read_b128 v[214:217], v140 offset:41472
	ds_read_b128 v[218:221], v140 offset:36896
	ds_read_b128 v[222:225], v141 offset:55328
	ds_read_b128 v[226:229], v141 offset:59936
	ds_read_b128 v[230:233], v140 offset:41504
	s_setprio 1
	s_waitcnt lgkmcnt(4)
	v_mfma_f32_32x32x16_bf16 v[50:65], v[158:161], v[162:165], v[50:65]
	v_mfma_f32_32x32x16_bf16 v[34:49], v[158:161], v[166:169], v[34:49]
	v_mfma_f32_32x32x16_bf16 v[18:33], v[214:217], v[162:165], v[18:33]
	v_mfma_f32_32x32x16_bf16 v[2:17], v[214:217], v[166:169], v[2:17]
	ds_read_b128 v[158:161], v140 offset:36928
	ds_read_b128 v[162:165], v141 offset:55360
	ds_read_b128 v[166:169], v141 offset:59968
	ds_read_b128 v[214:217], v140 offset:41536
	s_waitcnt lgkmcnt(4)
	v_mfma_f32_32x32x16_bf16 v[50:65], v[218:221], v[222:225], v[50:65]
	v_mfma_f32_32x32x16_bf16 v[34:49], v[218:221], v[226:229], v[34:49]
	v_mfma_f32_32x32x16_bf16 v[18:33], v[230:233], v[222:225], v[18:33]
	v_mfma_f32_32x32x16_bf16 v[2:17], v[230:233], v[226:229], v[2:17]
	ds_read_b128 v[218:221], v140 offset:36960
	ds_read_b128 v[222:225], v141 offset:55392
	ds_read_b128 v[226:229], v141 offset:60000
	ds_read_b128 v[230:233], v140 offset:41568
	s_waitcnt lgkmcnt(4)
	v_mfma_f32_32x32x16_bf16 v[50:65], v[158:161], v[162:165], v[50:65]
	v_mfma_f32_32x32x16_bf16 v[34:49], v[158:161], v[166:169], v[34:49]
	v_mfma_f32_32x32x16_bf16 v[18:33], v[214:217], v[162:165], v[18:33]
	v_mfma_f32_32x32x16_bf16 v[2:17], v[214:217], v[166:169], v[2:17]
	s_waitcnt lgkmcnt(0)
	v_mfma_f32_32x32x16_bf16 v[50:65], v[218:221], v[222:225], v[50:65]
	v_mfma_f32_32x32x16_bf16 v[34:49], v[218:221], v[226:229], v[34:49]
	v_mfma_f32_32x32x16_bf16 v[18:33], v[230:233], v[222:225], v[18:33]
	v_mfma_f32_32x32x16_bf16 v[2:17], v[230:233], v[226:229], v[2:17]
	s_setprio 0
	s_and_b64 vcc, exec, s[16:17]
	s_waitcnt vmcnt(8)
	ds_write_b128 v188, v[98:101]
	ds_write_b128 v188, v[102:105] offset:4608
	ds_write_b128 v188, v[106:109] offset:9216
	ds_write_b128 v188, v[110:113] offset:13824
	ds_write_b128 v188, v[114:117] offset:18432
	ds_write_b128 v188, v[118:121] offset:23040
	ds_write_b128 v188, v[122:125] offset:27648
	ds_write_b128 v188, v[126:129] offset:32256
	s_waitcnt lgkmcnt(0)
	s_barrier
	s_cbranch_vccnz .LBB0_600
	v_add_co_u32_e32 v102, vcc, 0x10000, v132
	global_load_dwordx4 v[98:101], v[132:133], off
	s_nop 0
	v_addc_co_u32_e32 v103, vcc, 0, v133, vcc
	v_add_co_u32_e32 v106, vcc, 0x20000, v132
	s_nop 1
	v_addc_co_u32_e32 v107, vcc, 0, v133, vcc
	v_add_co_u32_e32 v110, vcc, 0x30000, v132
	global_load_dwordx4 v[102:105], v[102:103], off
	s_nop 0
	global_load_dwordx4 v[106:109], v[106:107], off
	v_addc_co_u32_e32 v111, vcc, 0, v133, vcc
	v_add_co_u32_e32 v118, vcc, 0x10000, v134
	global_load_dwordx4 v[110:113], v[110:111], off
	s_nop 0
	global_load_dwordx4 v[114:117], v[134:135], off
	v_addc_co_u32_e32 v119, vcc, 0, v135, vcc
	v_add_co_u32_e32 v122, vcc, 0x20000, v134
	s_nop 1
	v_addc_co_u32_e32 v123, vcc, 0, v135, vcc
	v_add_co_u32_e32 v126, vcc, 0x30000, v134
	global_load_dwordx4 v[118:121], v[118:119], off
	s_nop 0
	global_load_dwordx4 v[122:125], v[122:123], off
	v_addc_co_u32_e32 v127, vcc, 0, v135, vcc
	global_load_dwordx4 v[126:129], v[126:127], off
; __device__ __forceinline__ void gemm_kstep(const u16* sb, int wn, int wt, int r, int h, f32x16 (&acc)[2][2]) {
;   const u16* bw = sb + (wn * 64 + r) * LDT + h * 8;
;   const u16* bx = sb + TILE_U16 + (wt * 64 + r) * LDT + h * 8;
;   __builtin_amdgcn_s_setprio(1);
; #pragma unroll
;   for (int ks = 0; ks < 4; ++ks) {
;     bf16x8 a0 = *(const bf16x8*)(bw + ks * 16);
;     bf16x8 a1 = *(const bf16x8*)(bw + 32 * LDT + ks * 16);
;     bf16x8 b0 = *(const bf16x8*)(bx + ks * 16);
;     bf16x8 b1 = *(const bf16x8*)(bx + 32 * LDT + ks * 16);
;     acc[0][0] = mfma32(a0, b0, acc[0][0]);
;     acc[0][1] = mfma32(a0, b1, acc[0][1]);
;     acc[1][0] = mfma32(a1, b0, acc[1][0]);
;     acc[1][1] = mfma32(a1, b1, acc[1][1]);
;   }
;   __builtin_amdgcn_s_setprio(0);
; }
; __device__ void gemm_phase(const u16* __restrict__ Wb, int ldw, const u16* __restrict__ Xb, int ldx, int K,
;                            u16* __restrict__ outb, int ldo, int ntn, int ntiles, u16* lds) {
;     ...
;       if (kt + 3 < nk) gs_load(A, gw, ldw, gx, ldx, (kt + 3) * 64);
;       else if (has_next) gs_load(A, gwn, ldw, gxn, ldx, 64);
;       gemm_kstep(lds + 2 * TILE_U16, wn, wt, r, h, acc);
;       if (kt + 2 < nk) gs_store(B, lds, lo);
;       __syncthreads();
.LBB0_600:
	ds_read_b128 v[158:161], v140
	ds_read_b128 v[162:165], v141 offset:18432
	ds_read_b128 v[166:169], v141 offset:23040
	ds_read_b128 v[214:217], v140 offset:4608
	ds_read_b128 v[218:221], v140 offset:32
	ds_read_b128 v[222:225], v141 offset:18464
	ds_read_b128 v[226:229], v141 offset:23072
	ds_read_b128 v[230:233], v140 offset:4640
	s_setprio 1
	s_waitcnt lgkmcnt(4)
	v_mfma_f32_32x32x16_bf16 v[50:65], v[158:161], v[162:165], v[50:65]
	v_mfma_f32_32x32x16_bf16 v[34:49], v[158:161], v[166:169], v[34:49]
	v_mfma_f32_32x32x16_bf16 v[18:33], v[214:217], v[162:165], v[18:33]
	v_mfma_f32_32x32x16_bf16 v[2:17], v[214:217], v[166:169], v[2:17]
	ds_read_b128 v[158:161], v140 offset:64
	ds_read_b128 v[162:165], v141 offset:18496
	ds_read_b128 v[166:169], v141 offset:23104
	ds_read_b128 v[214:217], v140 offset:4672
	s_waitcnt lgkmcnt(4)
	v_mfma_f32_32x32x16_bf16 v[50:65], v[218:221], v[222:225], v[50:65]
	v_mfma_f32_32x32x16_bf16 v[34:49], v[218:221], v[226:229], v[34:49]
	v_mfma_f32_32x32x16_bf16 v[18:33], v[230:233], v[222:225], v[18:33]
	v_mfma_f32_32x32x16_bf16 v[2:17], v[230:233], v[226:229], v[2:17]
	ds_read_b128 v[218:221], v140 offset:96
	ds_read_b128 v[222:225], v141 offset:18528
	ds_read_b128 v[226:229], v141 offset:23136
	ds_read_b128 v[230:233], v140 offset:4704
	s_waitcnt lgkmcnt(4)
	v_mfma_f32_32x32x16_bf16 v[50:65], v[158:161], v[162:165], v[50:65]
	v_mfma_f32_32x32x16_bf16 v[34:49], v[158:161], v[166:169], v[34:49]
	v_mfma_f32_32x32x16_bf16 v[18:33], v[214:217], v[162:165], v[18:33]
	v_mfma_f32_32x32x16_bf16 v[2:17], v[214:217], v[166:169], v[2:17]
	s_waitcnt lgkmcnt(0)
	v_mfma_f32_32x32x16_bf16 v[50:65], v[218:221], v[222:225], v[50:65]
	v_mfma_f32_32x32x16_bf16 v[34:49], v[218:221], v[226:229], v[34:49]
	v_mfma_f32_32x32x16_bf16 v[18:33], v[230:233], v[222:225], v[18:33]
	v_mfma_f32_32x32x16_bf16 v[2:17], v[230:233], v[226:229], v[2:17]
	s_setprio 0
	s_andn2_b64 vcc, exec, s[0:1]
	s_waitcnt vmcnt(0)
	ds_write_b128 v188, v[66:69] offset:36864
	ds_write_b128 v188, v[70:73] offset:41472
	ds_write_b128 v188, v[74:77] offset:46080
	ds_write_b128 v188, v[78:81] offset:50688
	ds_write_b128 v188, v[82:85] offset:55296
	ds_write_b128 v188, v[86:89] offset:59904
	ds_write_b128 v188, v[90:93] offset:64512
	ds_write_b128 v189, v[94:97] offset:13824
	s_waitcnt lgkmcnt(0)
	s_barrier
	s_cbranch_vccnz .LBB0_597
	v_add_co_u32_e32 v70, vcc, 0x10000, v132
	global_load_dwordx4 v[66:69], v[132:133], off offset:128
	s_nop 0
	v_addc_co_u32_e32 v71, vcc, 0, v133, vcc
	v_add_co_u32_e32 v74, vcc, 0x20000, v132
	s_nop 1
	v_addc_co_u32_e32 v75, vcc, 0, v133, vcc
	v_add_co_u32_e32 v78, vcc, 0x30000, v132
	global_load_dwordx4 v[70:73], v[70:71], off offset:128
	s_nop 0
	global_load_dwordx4 v[74:77], v[74:75], off offset:128
	v_addc_co_u32_e32 v79, vcc, 0, v133, vcc
	v_add_co_u32_e32 v86, vcc, 0x10000, v134
	global_load_dwordx4 v[78:81], v[78:79], off offset:128
	s_nop 0
	global_load_dwordx4 v[82:85], v[134:135], off offset:128
	v_addc_co_u32_e32 v87, vcc, 0, v135, vcc
	v_add_co_u32_e32 v90, vcc, 0x20000, v134
	s_nop 1
	v_addc_co_u32_e32 v91, vcc, 0, v135, vcc
	v_add_co_u32_e32 v94, vcc, 0x30000, v134
	global_load_dwordx4 v[86:89], v[86:87], off offset:128
	s_nop 0
	global_load_dwordx4 v[90:93], v[90:91], off offset:128
	v_addc_co_u32_e32 v95, vcc, 0, v135, vcc
	global_load_dwordx4 v[94:97], v[94:95], off offset:128
	s_branch .LBB0_597

; __device__ __forceinline__ int opaque_tid() { int t = threadIdx.x; asm volatile("" : "+v"(t)); return t; }
; __device__ __forceinline__ void gemm_kstep(const u16* sb, int wn, int wt, int r, int h, f32x16 (&acc)[2][2]) {
;   const u16* bw = sb + (wn * 64 + r) * LDT + h * 8;
;   const u16* bx = sb + TILE_U16 + (wt * 64 + r) * LDT + h * 8;
;   __builtin_amdgcn_s_setprio(1);
; #pragma unroll
;   for (int ks = 0; ks < 4; ++ks) {
;     bf16x8 a0 = *(const bf16x8*)(bw + ks * 16);
;     bf16x8 a1 = *(const bf16x8*)(bw + 32 * LDT + ks * 16);
;     bf16x8 b0 = *(const bf16x8*)(bx + ks * 16);
;     bf16x8 b1 = *(const bf16x8*)(bx + 32 * LDT + ks * 16);
;     acc[0][0] = mfma32(a0, b0, acc[0][0]);
;     acc[0][1] = mfma32(a0, b1, acc[0][1]);
;     acc[1][0] = mfma32(a1, b0, acc[1][0]);
;     acc[1][1] = mfma32(a1, b1, acc[1][1]);
;   }
;   __builtin_amdgcn_s_setprio(0);
; }
; __device__ __forceinline__ void stage_bf16(u16* st, f32x16 (&acc)[2][2]) {
;   const int tid = opaque_tid(), lane = tid & 63, w = tid >> 6, r = lane & 31, h = lane >> 5;
;   const int wn = w >> 1, wt = w & 1;
; #pragma unroll
;   for (int nb = 0; nb < 2; ++nb)
; #pragma unroll
;     for (int tb = 0; tb < 2; ++tb) {
;       const int token = wt * 64 + tb * 32 + r;
; #pragma unroll
;       for (int g = 0; g < 4; ++g) {
;         const int n0 = wn * 64 + nb * 32 + 8 * g + 4 * h;
;         uint2 v;
;         v.x = pack2(acc[nb][tb][4 * g], acc[nb][tb][4 * g + 1]);
;         v.y = pack2(acc[nb][tb][4 * g + 2], acc[nb][tb][4 * g + 3]);
;         *(uint2*)(st + token * 136 + n0) = v;
;       }
;     }
; }
; __device__ void gemm_phase(const u16* __restrict__ Wb, int ldw, const u16* __restrict__ Xb, int ldx, int K,
;                            u16* __restrict__ outb, int ldo, int ntn, int ntiles, u16* lds) {
;     ...
;       gemm_kstep(lds + 2 * TILE_U16, wn, wt, r, h, acc);
;       if (kt + 2 < nk) gs_store(B, lds, lo);
;       __syncthreads();
;     }
;     stage_bf16(lds, acc);
;     __syncthreads();
;     u16* out = outb + (size_t)GP_MT(q) * 128 * ldo + GP_NT(q) * 128;
; #pragma unroll
;     for (int i = 0; i < 8; ++i) {
;       const int id = tid + 256 * i;
;       const int row = id >> 4, c = id & 15;
;       uint4 v = *(const uint4*)(lds + row * 136 + c * 8);
;       *(uint4*)(out + (size_t)row * ldo + c * 8) = v;
;     }
;     __syncthreads();
.LBB0_608:
	ds_read_b128 v[158:161], v140 offset:36864
	ds_read_b128 v[162:165], v141 offset:55296
	ds_read_b128 v[166:169], v141 offset:59904
	ds_read_b128 v[214:217], v140 offset:41472
	ds_read_b128 v[218:221], v140 offset:36896
	ds_read_b128 v[222:225], v141 offset:55328
	ds_read_b128 v[226:229], v141 offset:59936
	ds_read_b128 v[230:233], v140 offset:41504
	s_setprio 1
	s_waitcnt lgkmcnt(4)
	v_mfma_f32_32x32x16_bf16 v[50:65], v[158:161], v[162:165], v[50:65]
	v_mfma_f32_32x32x16_bf16 v[34:49], v[158:161], v[166:169], v[34:49]
	v_mfma_f32_32x32x16_bf16 v[18:33], v[214:217], v[162:165], v[18:33]
	v_mfma_f32_32x32x16_bf16 v[2:17], v[214:217], v[166:169], v[2:17]
	ds_read_b128 v[158:161], v140 offset:36928
	ds_read_b128 v[162:165], v141 offset:55360
	ds_read_b128 v[166:169], v141 offset:59968
	ds_read_b128 v[214:217], v140 offset:41536
	s_waitcnt lgkmcnt(4)
	v_mfma_f32_32x32x16_bf16 v[50:65], v[218:221], v[222:225], v[50:65]
	v_mfma_f32_32x32x16_bf16 v[34:49], v[218:221], v[226:229], v[34:49]
	v_mfma_f32_32x32x16_bf16 v[18:33], v[230:233], v[222:225], v[18:33]
	v_mfma_f32_32x32x16_bf16 v[2:17], v[230:233], v[226:229], v[2:17]
	ds_read_b128 v[218:221], v140 offset:36960
	ds_read_b128 v[222:225], v141 offset:55392
	ds_read_b128 v[226:229], v141 offset:60000
	ds_read_b128 v[230:233], v140 offset:41568
	s_waitcnt lgkmcnt(4)
	v_mfma_f32_32x32x16_bf16 v[50:65], v[158:161], v[162:165], v[50:65]
	v_mfma_f32_32x32x16_bf16 v[34:49], v[158:161], v[166:169], v[34:49]
	v_mfma_f32_32x32x16_bf16 v[18:33], v[214:217], v[162:165], v[18:33]
	v_mfma_f32_32x32x16_bf16 v[2:17], v[214:217], v[166:169], v[2:17]
	s_waitcnt lgkmcnt(0)
	v_mfma_f32_32x32x16_bf16 v[50:65], v[218:221], v[222:225], v[50:65]
	v_mfma_f32_32x32x16_bf16 v[34:49], v[218:221], v[226:229], v[34:49]
	v_mfma_f32_32x32x16_bf16 v[18:33], v[230:233], v[222:225], v[18:33]
	v_mfma_f32_32x32x16_bf16 v[2:17], v[230:233], v[226:229], v[2:17]
	s_setprio 0
	v_mov_b32_e32 v158, v174
	s_lshr_b32 s38, s41, 3
	s_barrier
	s_and_b32 s38, s38, 0xffffff8
	v_lshrrev_b32_e32 v160, 2, v158
	v_and_b32_e32 v160, 8, v160
	s_add_i32 s38, s38, s18
	s_and_b32 s39, s41, 7
	v_and_b32_e32 v159, 0x5f, v158
	v_and_or_b32 v158, v158, s29, v160
	s_or_b32 s82, s38, s39
	v_mad_u32_u24 v158, v159, s28, v158
	s_lshl_b64 s[38:39], s[82:83], 18
	v_cvt_pk_bf16_f32 v53, v52, v53
	v_cvt_pk_bf16_f32 v52, v50, v51
	v_cvt_pk_bf16_f32 v51, v56, v57
	v_cvt_pk_bf16_f32 v50, v54, v55
	v_cvt_pk_bf16_f32 v37, v36, v37
	v_cvt_pk_bf16_f32 v36, v34, v35
	v_cvt_pk_bf16_f32 v35, v40, v41
	v_cvt_pk_bf16_f32 v34, v38, v39
	v_add_u32_e32 v38, 0x2000, v158
	v_cvt_pk_bf16_f32 v21, v20, v21
	v_cvt_pk_bf16_f32 v20, v18, v19
	v_cvt_pk_bf16_f32 v19, v24, v25
	v_cvt_pk_bf16_f32 v18, v22, v23
	v_cvt_pk_bf16_f32 v5, v4, v5
	v_cvt_pk_bf16_f32 v4, v2, v3
	v_cvt_pk_bf16_f32 v3, v8, v9
	v_cvt_pk_bf16_f32 v2, v6, v7
	s_add_u32 s38, s16, s38
	ds_write2_b64 v158, v[52:53], v[50:51] offset1:2
	v_cvt_pk_bf16_f32 v51, v60, v61
	v_cvt_pk_bf16_f32 v50, v58, v59
	v_cvt_pk_bf16_f32 v53, v64, v65
	v_cvt_pk_bf16_f32 v52, v62, v63
	ds_write2_b64 v38, v[36:37], v[34:35] offset0:64 offset1:66
	v_cvt_pk_bf16_f32 v35, v44, v45
	v_cvt_pk_bf16_f32 v34, v42, v43
	v_cvt_pk_bf16_f32 v37, v48, v49
	v_cvt_pk_bf16_f32 v36, v46, v47
	ds_write2_b64 v158, v[20:21], v[18:19] offset0:8 offset1:10
	v_cvt_pk_bf16_f32 v19, v28, v29
	v_cvt_pk_bf16_f32 v18, v26, v27
	v_cvt_pk_bf16_f32 v21, v32, v33
	v_cvt_pk_bf16_f32 v20, v30, v31
	ds_write2_b64 v38, v[4:5], v[2:3] offset0:72 offset1:74
	v_cvt_pk_bf16_f32 v3, v12, v13
	v_cvt_pk_bf16_f32 v2, v10, v11
	v_cvt_pk_bf16_f32 v5, v16, v17
	v_cvt_pk_bf16_f32 v4, v14, v15
	s_addc_u32 s39, s17, s39
	s_and_b32 s41, s40, 0x380
	ds_write2_b64 v158, v[50:51], v[52:53] offset0:4 offset1:6
	ds_write2_b64 v38, v[34:35], v[36:37] offset0:68 offset1:70
	ds_write2_b64 v158, v[18:19], v[20:21] offset0:12 offset1:14
	ds_write2_b64 v38, v[2:3], v[4:5] offset0:76 offset1:78
	s_waitcnt lgkmcnt(0)
	s_barrier
	s_lshl_b32 s41, s41, 1
	ds_read_b128 v[2:5], v190
	ds_read_b128 v[6:9], v191
	s_add_u32 s38, s38, s41
	s_addc_u32 s39, s39, 0
	v_lshl_add_u64 v[14:15], s[38:39], 0, v[0:1]
	v_lshl_add_u64 v[10:11], v[14:15], 0, v[142:143]
	s_waitcnt lgkmcnt(1)
	global_store_dwordx4 v[10:11], v[2:5], off
	ds_read_b128 v[2:5], v192
	v_lshl_add_u64 v[10:11], v[14:15], 0, v[144:145]
	s_waitcnt lgkmcnt(1)
	global_store_dwordx4 v[10:11], v[6:9], off
	ds_read_b128 v[6:9], v193
	v_lshl_add_u64 v[10:11], v[14:15], 0, v[146:147]
	s_waitcnt lgkmcnt(1)
	global_store_dwordx4 v[10:11], v[2:5], off
	ds_read_b128 v[2:5], v194
	v_lshl_add_u64 v[10:11], v[14:15], 0, v[148:149]
	s_waitcnt lgkmcnt(1)
	global_store_dwordx4 v[10:11], v[6:9], off
	v_lshl_add_u64 v[10:11], v[14:15], 0, v[150:151]
	ds_read_b128 v[6:9], v195
	s_waitcnt lgkmcnt(1)
	global_store_dwordx4 v[10:11], v[2:5], off
	ds_read_b128 v[2:5], v196
	ds_read_b128 v[10:13], v197
	v_lshl_add_u64 v[16:17], v[14:15], 0, v[152:153]
	s_waitcnt lgkmcnt(2)
	global_store_dwordx4 v[16:17], v[6:9], off
	s_add_i32 s40, s40, s77
	s_and_b64 vcc, exec, s[0:1]
	v_lshl_add_u64 v[6:7], v[14:15], 0, v[154:155]
	s_waitcnt lgkmcnt(1)
	global_store_dwordx4 v[6:7], v[2:5], off
	s_mov_b32 s41, s42
	s_nop 0
	v_lshl_add_u64 v[2:3], v[14:15], 0, v[156:157]
	s_waitcnt lgkmcnt(0)
	global_store_dwordx4 v[2:3], v[10:13], off
	s_barrier
	s_cbranch_vccnz .LBB0_613
; __device__ __forceinline__ void gemm_kstep(const u16* sb, int wn, int wt, int r, int h, f32x16 (&acc)[2][2]) {
;   const u16* bw = sb + (wn * 64 + r) * LDT + h * 8;
;   const u16* bx = sb + TILE_U16 + (wt * 64 + r) * LDT + h * 8;
;   __builtin_amdgcn_s_setprio(1);
; #pragma unroll
;   for (int ks = 0; ks < 4; ++ks) {
;     bf16x8 a0 = *(const bf16x8*)(bw + ks * 16);
;     bf16x8 a1 = *(const bf16x8*)(bw + 32 * LDT + ks * 16);
;     bf16x8 b0 = *(const bf16x8*)(bx + ks * 16);
;     bf16x8 b1 = *(const bf16x8*)(bx + 32 * LDT + ks * 16);
;     acc[0][0] = mfma32(a0, b0, acc[0][0]);
;     acc[0][1] = mfma32(a0, b1, acc[0][1]);
;     acc[1][0] = mfma32(a1, b0, acc[1][0]);
;     acc[1][1] = mfma32(a1, b1, acc[1][1]);
;   }
;   __builtin_amdgcn_s_setprio(0);
; }
; __device__ void gemm_phase(const u16* __restrict__ Wb, int ldw, const u16* __restrict__ Xb, int ldx, int K,
;                            u16* __restrict__ outb, int ldo, int ntn, int ntiles, u16* lds) {
;     ...
;   for (; q < L; q += nbl) {
;     const int qn = q + nbl;
;     const bool has_next = qn < L;
;     const int qq = has_next ? qn : q;
;     const u16* gwn = Wb + (size_t)(GP_NT(qq) * 128 + lrow) * ldw + lc * 8;
;     const u16* gxn = Xb + (size_t)(GP_MT(qq) * 128 + lrow) * ldx + lc * 8;
;     f32x16 acc[2][2];
; #pragma unroll
;     for (int a = 0; a < 2; ++a)
; #pragma unroll
;       for (int b = 0; b < 2; ++b)
; #pragma unroll
;         for (int i = 0; i < 16; ++i) acc[a][b][i] = 0.f;
;     gs_store(B, lds, lo);
;     __syncthreads();
;     for (int kt = 0; kt < nk; kt += 2) {
;       if (kt + 2 < nk) gs_load(B, gw, ldw, gx, ldx, (kt + 2) * 64);
;       else if (has_next) gs_load(B, gwn, ldw, gxn, ldx, 0);
;       gemm_kstep(lds, wn, wt, r, h, acc);
;       gs_store(A, lds + 2 * TILE_U16, lo);
;       __syncthreads();
.LBB0_609:
	v_mov_b64_e32 v[160:161], v[132:133]
	v_add_co_u32_e32 v162, vcc, s81, v160
	v_mov_b64_e32 v[158:159], v[134:135]
	s_nop 0
	v_addc_co_u32_e32 v163, vcc, 0, v161, vcc
	v_add_co_u32_e32 v164, vcc, s80, v160
	s_waitcnt vmcnt(1)
	ds_write_b128 v188, v[86:89]
	ds_write_b128 v188, v[98:101] offset:4608
	ds_write_b128 v188, v[102:105] offset:9216
	ds_write_b128 v188, v[110:113] offset:13824
	ds_write_b128 v188, v[114:117] offset:18432
	ds_write_b128 v188, v[118:121] offset:23040
	ds_write_b128 v188, v[122:125] offset:27648
	ds_write_b128 v188, v[126:129] offset:32256
	v_addc_co_u32_e32 v165, vcc, 0, v161, vcc
	v_add_co_u32_e32 v166, vcc, s84, v160
	s_waitcnt lgkmcnt(0)
	s_nop 0
	v_addc_co_u32_e32 v167, vcc, 0, v161, vcc
	v_add_co_u32_e32 v168, vcc, s81, v158
	s_barrier
	s_nop 0
	v_addc_co_u32_e32 v169, vcc, 0, v159, vcc
	v_add_co_u32_e32 v170, vcc, s80, v158
	s_nop 1
	v_addc_co_u32_e32 v171, vcc, 0, v159, vcc
	v_add_co_u32_e32 v172, vcc, s84, v158
	global_load_dwordx4 v[86:89], v[132:133], off offset:256
	s_nop 0
	v_addc_co_u32_e32 v173, vcc, 0, v159, vcc
	global_load_dwordx4 v[98:101], v[162:163], off offset:256
	global_load_dwordx4 v[102:105], v[164:165], off offset:256
	global_load_dwordx4 v[110:113], v[166:167], off offset:256
	global_load_dwordx4 v[114:117], v[134:135], off offset:256
	global_load_dwordx4 v[118:121], v[168:169], off offset:256
	global_load_dwordx4 v[122:125], v[170:171], off offset:256
	global_load_dwordx4 v[126:129], v[172:173], off offset:256
	s_add_i32 s42, s41, s87
	s_cmpk_gt_u32 s42, 0xff
	s_cselect_b64 s[0:1], -1, 0
	s_cmpk_lt_u32 s42, 0x100
	s_cselect_b64 s[38:39], -1, 0
	s_and_b64 s[44:45], s[38:39], exec
	s_cselect_b32 s43, s42, s41
	s_lshl_b32 s44, s43, 4
	s_and_b32 s43, s43, 7
	s_or_b32 s43, s43, s18
	s_and_b32 s45, s44, 0x380
	s_and_b32 s44, s44, 0xfffffc00
	s_lshl_b32 s43, s43, 7
	s_add_i32 s43, s43, s44
	v_add_u32_e32 v2, s45, v131
	v_add_u32_e32 v4, s43, v131
	v_ashrrev_i32_e32 v3, 31, v2
	v_ashrrev_i32_e32 v5, 31, v4
	v_lshlrev_b64 v[2:3], 11, v[2:3]
	v_lshlrev_b64 v[4:5], 11, v[4:5]
	v_lshl_add_u64 v[132:133], v[136:137], 0, v[2:3]
	v_lshl_add_u64 v[134:135], v[138:139], 0, v[4:5]
	s_setprio 1
	ds_read_b128 v[2:5], v140
	ds_read_b128 v[6:9], v141 offset:18432
	ds_read_b128 v[10:13], v141 offset:23040
	s_waitcnt lgkmcnt(1)
	v_mfma_f32_32x32x16_bf16 v[50:65], v[2:5], v[6:9], 0
	s_waitcnt lgkmcnt(0)
	v_mfma_f32_32x32x16_bf16 v[34:49], v[2:5], v[10:13], 0
	ds_read_b128 v[2:5], v140 offset:4608
	ds_read_b128 v[198:201], v140 offset:32
	ds_read_b128 v[202:205], v141 offset:18464
	ds_read_b128 v[206:209], v141 offset:23072
	s_waitcnt lgkmcnt(1)
	v_mfma_f32_32x32x16_bf16 v[50:65], v[198:201], v[202:205], v[50:65]
	s_waitcnt lgkmcnt(0)
	v_mfma_f32_32x32x16_bf16 v[34:49], v[198:201], v[206:209], v[34:49]
	ds_read_b128 v[198:201], v140 offset:4640
	v_mfma_f32_32x32x16_bf16 v[18:33], v[2:5], v[6:9], 0
	v_mfma_f32_32x32x16_bf16 v[2:17], v[2:5], v[10:13], 0
	s_waitcnt lgkmcnt(0)
	v_mfma_f32_32x32x16_bf16 v[18:33], v[198:201], v[202:205], v[18:33]
	v_mfma_f32_32x32x16_bf16 v[2:17], v[198:201], v[206:209], v[2:17]
	ds_read_b128 v[198:201], v140 offset:64
	ds_read_b128 v[202:205], v141 offset:18496
	ds_read_b128 v[206:209], v141 offset:23104
	s_waitcnt lgkmcnt(1)
	v_mfma_f32_32x32x16_bf16 v[50:65], v[198:201], v[202:205], v[50:65]
	s_waitcnt lgkmcnt(0)
	v_mfma_f32_32x32x16_bf16 v[34:49], v[198:201], v[206:209], v[34:49]
	ds_read_b128 v[198:201], v140 offset:4672
	s_waitcnt lgkmcnt(0)
	v_mfma_f32_32x32x16_bf16 v[18:33], v[198:201], v[202:205], v[18:33]
	v_mfma_f32_32x32x16_bf16 v[2:17], v[198:201], v[206:209], v[2:17]
	ds_read_b128 v[198:201], v140 offset:96
	ds_read_b128 v[202:205], v141 offset:18528
	ds_read_b128 v[206:209], v141 offset:23136
	s_waitcnt lgkmcnt(1)
	v_mfma_f32_32x32x16_bf16 v[50:65], v[198:201], v[202:205], v[50:65]
	s_waitcnt lgkmcnt(0)
	v_mfma_f32_32x32x16_bf16 v[34:49], v[198:201], v[206:209], v[34:49]
	ds_read_b128 v[198:201], v140 offset:4704
	s_waitcnt lgkmcnt(0)
	v_mfma_f32_32x32x16_bf16 v[18:33], v[198:201], v[202:205], v[18:33]
	v_mfma_f32_32x32x16_bf16 v[2:17], v[198:201], v[206:209], v[2:17]
	s_setprio 0
	ds_write_b128 v188, v[66:69] offset:36864
	ds_write_b128 v188, v[70:73] offset:41472
	ds_write_b128 v188, v[74:77] offset:46080
	ds_write_b128 v188, v[78:81] offset:50688
	ds_write_b128 v188, v[82:85] offset:55296
	ds_write_b128 v188, v[90:93] offset:59904
	ds_write_b128 v188, v[94:97] offset:64512
	s_waitcnt vmcnt(8)
	ds_write_b128 v189, v[106:109] offset:13824
	s_waitcnt lgkmcnt(0)
	s_barrier
; __device__ __forceinline__ void gemm_kstep(const u16* sb, int wn, int wt, int r, int h, f32x16 (&acc)[2][2]) {
;   const u16* bw = sb + (wn * 64 + r) * LDT + h * 8;
;   const u16* bx = sb + TILE_U16 + (wt * 64 + r) * LDT + h * 8;
;   __builtin_amdgcn_s_setprio(1);
; #pragma unroll
;   for (int ks = 0; ks < 4; ++ks) {
;     bf16x8 a0 = *(const bf16x8*)(bw + ks * 16);
;     bf16x8 a1 = *(const bf16x8*)(bw + 32 * LDT + ks * 16);
;     bf16x8 b0 = *(const bf16x8*)(bx + ks * 16);
;     bf16x8 b1 = *(const bf16x8*)(bx + 32 * LDT + ks * 16);
;     acc[0][0] = mfma32(a0, b0, acc[0][0]);
;     acc[0][1] = mfma32(a0, b1, acc[0][1]);
;     acc[1][0] = mfma32(a1, b0, acc[1][0]);
;     acc[1][1] = mfma32(a1, b1, acc[1][1]);
;   }
;   __builtin_amdgcn_s_setprio(0);
; }
; __device__ void gemm_phase(const u16* __restrict__ Wb, int ldw, const u16* __restrict__ Xb, int ldx, int K,
;                            u16* __restrict__ outb, int ldo, int ntn, int ntiles, u16* lds) {
;     ...
;     for (int kt = 0; kt < nk; kt += 2) {
;       if (kt + 2 < nk) gs_load(B, gw, ldw, gx, ldx, (kt + 2) * 64);
;       else if (has_next) gs_load(B, gwn, ldw, gxn, ldx, 0);
;       gemm_kstep(lds, wn, wt, r, h, acc);
;       gs_store(A, lds + 2 * TILE_U16, lo);
;       __syncthreads();
;       if (kt + 3 < nk) gs_load(A, gw, ldw, gx, ldx, (kt + 3) * 64);
;       else if (has_next) gs_load(A, gwn, ldw, gxn, ldx, 64);
;       gemm_kstep(lds + 2 * TILE_U16, wn, wt, r, h, acc);
;       if (kt + 2 < nk) gs_store(B, lds, lo);
;       __syncthreads();
;     }
	ds_read_b128 v[198:201], v140 offset:36864
	ds_read_b128 v[202:205], v141 offset:55296
	ds_read_b128 v[206:209], v141 offset:59904
	ds_read_b128 v[214:217], v140 offset:41472
	ds_read_b128 v[218:221], v140 offset:36896
	ds_read_b128 v[222:225], v141 offset:55328
	ds_read_b128 v[226:229], v141 offset:59936
	ds_read_b128 v[230:233], v140 offset:41504
	s_setprio 1
	s_waitcnt lgkmcnt(4)
	v_mfma_f32_32x32x16_bf16 v[50:65], v[198:201], v[202:205], v[50:65]
	v_mfma_f32_32x32x16_bf16 v[34:49], v[198:201], v[206:209], v[34:49]
	v_mfma_f32_32x32x16_bf16 v[18:33], v[214:217], v[202:205], v[18:33]
	v_mfma_f32_32x32x16_bf16 v[2:17], v[214:217], v[206:209], v[2:17]
	global_load_dwordx4 v[66:69], v[160:161], off offset:384
	global_load_dwordx4 v[70:73], v[162:163], off offset:384
	global_load_dwordx4 v[74:77], v[164:165], off offset:384
	global_load_dwordx4 v[78:81], v[166:167], off offset:384
	global_load_dwordx4 v[82:85], v[158:159], off offset:384
	global_load_dwordx4 v[90:93], v[168:169], off offset:384
	global_load_dwordx4 v[94:97], v[170:171], off offset:384
	global_load_dwordx4 v[106:109], v[172:173], off offset:384
	ds_read_b128 v[198:201], v140 offset:36928
	ds_read_b128 v[202:205], v141 offset:55360
	ds_read_b128 v[206:209], v141 offset:59968
	ds_read_b128 v[214:217], v140 offset:41536
	s_waitcnt lgkmcnt(4)
	v_mfma_f32_32x32x16_bf16 v[50:65], v[218:221], v[222:225], v[50:65]
	v_mfma_f32_32x32x16_bf16 v[34:49], v[218:221], v[226:229], v[34:49]
	v_mfma_f32_32x32x16_bf16 v[18:33], v[230:233], v[222:225], v[18:33]
	v_mfma_f32_32x32x16_bf16 v[2:17], v[230:233], v[226:229], v[2:17]
	ds_read_b128 v[218:221], v140 offset:36960
	ds_read_b128 v[222:225], v141 offset:55392
	ds_read_b128 v[226:229], v141 offset:60000
	ds_read_b128 v[230:233], v140 offset:41568
	s_waitcnt lgkmcnt(4)
	v_mfma_f32_32x32x16_bf16 v[50:65], v[198:201], v[202:205], v[50:65]
	v_mfma_f32_32x32x16_bf16 v[34:49], v[198:201], v[206:209], v[34:49]
	v_mfma_f32_32x32x16_bf16 v[18:33], v[214:217], v[202:205], v[18:33]
	v_mfma_f32_32x32x16_bf16 v[2:17], v[214:217], v[206:209], v[2:17]
	s_waitcnt lgkmcnt(0)
	v_mfma_f32_32x32x16_bf16 v[50:65], v[218:221], v[222:225], v[50:65]
	v_mfma_f32_32x32x16_bf16 v[34:49], v[218:221], v[226:229], v[34:49]
	v_mfma_f32_32x32x16_bf16 v[18:33], v[230:233], v[222:225], v[18:33]
	v_mfma_f32_32x32x16_bf16 v[2:17], v[230:233], v[226:229], v[2:17]
	s_setprio 0
	s_waitcnt vmcnt(8)
	ds_write_b128 v188, v[86:89]
	ds_write_b128 v188, v[98:101] offset:4608
	ds_write_b128 v188, v[102:105] offset:9216
	ds_write_b128 v188, v[110:113] offset:13824
	ds_write_b128 v188, v[114:117] offset:18432
	ds_write_b128 v188, v[118:121] offset:23040
	ds_write_b128 v188, v[122:125] offset:27648
	ds_write_b128 v188, v[126:129] offset:32256
	s_waitcnt lgkmcnt(0)
	s_barrier
	ds_read_b128 v[198:201], v140
	ds_read_b128 v[202:205], v141 offset:18432
	ds_read_b128 v[206:209], v141 offset:23040
	ds_read_b128 v[214:217], v140 offset:4608
	ds_read_b128 v[218:221], v140 offset:32
	ds_read_b128 v[222:225], v141 offset:18464
	ds_read_b128 v[226:229], v141 offset:23072
	ds_read_b128 v[230:233], v140 offset:4640
	s_setprio 1
	s_waitcnt lgkmcnt(4)
	v_mfma_f32_32x32x16_bf16 v[50:65], v[198:201], v[202:205], v[50:65]
	v_mfma_f32_32x32x16_bf16 v[34:49], v[198:201], v[206:209], v[34:49]
	v_mfma_f32_32x32x16_bf16 v[18:33], v[214:217], v[202:205], v[18:33]
	v_mfma_f32_32x32x16_bf16 v[2:17], v[214:217], v[206:209], v[2:17]
	global_load_dwordx4 v[86:89], v[160:161], off offset:512
	global_load_dwordx4 v[98:101], v[162:163], off offset:512
	global_load_dwordx4 v[102:105], v[164:165], off offset:512
	global_load_dwordx4 v[110:113], v[166:167], off offset:512
	global_load_dwordx4 v[114:117], v[158:159], off offset:512
	global_load_dwordx4 v[118:121], v[168:169], off offset:512
	global_load_dwordx4 v[122:125], v[170:171], off offset:512
	global_load_dwordx4 v[126:129], v[172:173], off offset:512
	ds_read_b128 v[198:201], v140 offset:64
	ds_read_b128 v[202:205], v141 offset:18496
	ds_read_b128 v[206:209], v141 offset:23104
	ds_read_b128 v[214:217], v140 offset:4672
	s_waitcnt lgkmcnt(4)
	v_mfma_f32_32x32x16_bf16 v[50:65], v[218:221], v[222:225], v[50:65]
	v_mfma_f32_32x32x16_bf16 v[34:49], v[218:221], v[226:229], v[34:49]
	v_mfma_f32_32x32x16_bf16 v[18:33], v[230:233], v[222:225], v[18:33]
	v_mfma_f32_32x32x16_bf16 v[2:17], v[230:233], v[226:229], v[2:17]
	ds_read_b128 v[218:221], v140 offset:96
	ds_read_b128 v[222:225], v141 offset:18528
	ds_read_b128 v[226:229], v141 offset:23136
	ds_read_b128 v[230:233], v140 offset:4704
	s_waitcnt lgkmcnt(4)
	v_mfma_f32_32x32x16_bf16 v[50:65], v[198:201], v[202:205], v[50:65]
	v_mfma_f32_32x32x16_bf16 v[34:49], v[198:201], v[206:209], v[34:49]
	v_mfma_f32_32x32x16_bf16 v[18:33], v[214:217], v[202:205], v[18:33]
	v_mfma_f32_32x32x16_bf16 v[2:17], v[214:217], v[206:209], v[2:17]
	s_waitcnt lgkmcnt(0)
	v_mfma_f32_32x32x16_bf16 v[50:65], v[218:221], v[222:225], v[50:65]
	v_mfma_f32_32x32x16_bf16 v[34:49], v[218:221], v[226:229], v[34:49]
	v_mfma_f32_32x32x16_bf16 v[18:33], v[230:233], v[222:225], v[18:33]
	v_mfma_f32_32x32x16_bf16 v[2:17], v[230:233], v[226:229], v[2:17]
	s_setprio 0
	s_waitcnt vmcnt(8)
	ds_write_b128 v188, v[66:69] offset:36864
	ds_write_b128 v188, v[70:73] offset:41472
	ds_write_b128 v188, v[74:77] offset:46080
	ds_write_b128 v188, v[78:81] offset:50688
	ds_write_b128 v188, v[82:85] offset:55296
	ds_write_b128 v188, v[90:93] offset:59904
	ds_write_b128 v188, v[94:97] offset:64512
	ds_write_b128 v189, v[106:109] offset:13824
	s_waitcnt lgkmcnt(0)
	s_barrier
; __device__ __forceinline__ void gemm_kstep(const u16* sb, int wn, int wt, int r, int h, f32x16 (&acc)[2][2]) {
;   const u16* bw = sb + (wn * 64 + r) * LDT + h * 8;
;   const u16* bx = sb + TILE_U16 + (wt * 64 + r) * LDT + h * 8;
;   __builtin_amdgcn_s_setprio(1);
; #pragma unroll
;   for (int ks = 0; ks < 4; ++ks) {
;     bf16x8 a0 = *(const bf16x8*)(bw + ks * 16);
;     bf16x8 a1 = *(const bf16x8*)(bw + 32 * LDT + ks * 16);
;     bf16x8 b0 = *(const bf16x8*)(bx + ks * 16);
;     bf16x8 b1 = *(const bf16x8*)(bx + 32 * LDT + ks * 16);
;     acc[0][0] = mfma32(a0, b0, acc[0][0]);
;     acc[0][1] = mfma32(a0, b1, acc[0][1]);
;     acc[1][0] = mfma32(a1, b0, acc[1][0]);
;     acc[1][1] = mfma32(a1, b1, acc[1][1]);
;   }
;   __builtin_amdgcn_s_setprio(0);
; }
; __device__ void gemm_phase(const u16* __restrict__ Wb, int ldw, const u16* __restrict__ Xb, int ldx, int K,
;                            u16* __restrict__ outb, int ldo, int ntn, int ntiles, u16* lds) {
;     ...
;     for (int kt = 0; kt < nk; kt += 2) {
;       if (kt + 2 < nk) gs_load(B, gw, ldw, gx, ldx, (kt + 2) * 64);
;       else if (has_next) gs_load(B, gwn, ldw, gxn, ldx, 0);
;       gemm_kstep(lds, wn, wt, r, h, acc);
;       gs_store(A, lds + 2 * TILE_U16, lo);
;       __syncthreads();
;       if (kt + 3 < nk) gs_load(A, gw, ldw, gx, ldx, (kt + 3) * 64);
;       else if (has_next) gs_load(A, gwn, ldw, gxn, ldx, 64);
;       gemm_kstep(lds + 2 * TILE_U16, wn, wt, r, h, acc);
;       if (kt + 2 < nk) gs_store(B, lds, lo);
;       __syncthreads();
;     }
	ds_read_b128 v[198:201], v140 offset:36864
	ds_read_b128 v[202:205], v141 offset:55296
	ds_read_b128 v[206:209], v141 offset:59904
	ds_read_b128 v[214:217], v140 offset:41472
	ds_read_b128 v[218:221], v140 offset:36896
	ds_read_b128 v[222:225], v141 offset:55328
	ds_read_b128 v[226:229], v141 offset:59936
	ds_read_b128 v[230:233], v140 offset:41504
	s_setprio 1
	s_waitcnt lgkmcnt(4)
	v_mfma_f32_32x32x16_bf16 v[50:65], v[198:201], v[202:205], v[50:65]
	v_mfma_f32_32x32x16_bf16 v[34:49], v[198:201], v[206:209], v[34:49]
	v_mfma_f32_32x32x16_bf16 v[18:33], v[214:217], v[202:205], v[18:33]
	v_mfma_f32_32x32x16_bf16 v[2:17], v[214:217], v[206:209], v[2:17]
	global_load_dwordx4 v[66:69], v[160:161], off offset:640
	global_load_dwordx4 v[70:73], v[162:163], off offset:640
	global_load_dwordx4 v[74:77], v[164:165], off offset:640
	global_load_dwordx4 v[78:81], v[166:167], off offset:640
	global_load_dwordx4 v[82:85], v[158:159], off offset:640
	global_load_dwordx4 v[90:93], v[168:169], off offset:640
	global_load_dwordx4 v[94:97], v[170:171], off offset:640
	global_load_dwordx4 v[106:109], v[172:173], off offset:640
	ds_read_b128 v[198:201], v140 offset:36928
	ds_read_b128 v[202:205], v141 offset:55360
	ds_read_b128 v[206:209], v141 offset:59968
	ds_read_b128 v[214:217], v140 offset:41536
	s_waitcnt lgkmcnt(4)
	v_mfma_f32_32x32x16_bf16 v[50:65], v[218:221], v[222:225], v[50:65]
	v_mfma_f32_32x32x16_bf16 v[34:49], v[218:221], v[226:229], v[34:49]
	v_mfma_f32_32x32x16_bf16 v[18:33], v[230:233], v[222:225], v[18:33]
	v_mfma_f32_32x32x16_bf16 v[2:17], v[230:233], v[226:229], v[2:17]
	ds_read_b128 v[218:221], v140 offset:36960
	ds_read_b128 v[222:225], v141 offset:55392
	ds_read_b128 v[226:229], v141 offset:60000
	ds_read_b128 v[230:233], v140 offset:41568
	s_waitcnt lgkmcnt(4)
	v_mfma_f32_32x32x16_bf16 v[50:65], v[198:201], v[202:205], v[50:65]
	v_mfma_f32_32x32x16_bf16 v[34:49], v[198:201], v[206:209], v[34:49]
	v_mfma_f32_32x32x16_bf16 v[18:33], v[214:217], v[202:205], v[18:33]
	v_mfma_f32_32x32x16_bf16 v[2:17], v[214:217], v[206:209], v[2:17]
	s_waitcnt lgkmcnt(0)
	v_mfma_f32_32x32x16_bf16 v[50:65], v[218:221], v[222:225], v[50:65]
	v_mfma_f32_32x32x16_bf16 v[34:49], v[218:221], v[226:229], v[34:49]
	v_mfma_f32_32x32x16_bf16 v[18:33], v[230:233], v[222:225], v[18:33]
	v_mfma_f32_32x32x16_bf16 v[2:17], v[230:233], v[226:229], v[2:17]
	s_setprio 0
	s_waitcnt vmcnt(8)
	ds_write_b128 v188, v[86:89]
	ds_write_b128 v188, v[98:101] offset:4608
	ds_write_b128 v188, v[102:105] offset:9216
	ds_write_b128 v188, v[110:113] offset:13824
	ds_write_b128 v188, v[114:117] offset:18432
	ds_write_b128 v188, v[118:121] offset:23040
	ds_write_b128 v188, v[122:125] offset:27648
	ds_write_b128 v188, v[126:129] offset:32256
	s_waitcnt lgkmcnt(0)
	s_barrier
	ds_read_b128 v[198:201], v140
	ds_read_b128 v[202:205], v141 offset:18432
	ds_read_b128 v[206:209], v141 offset:23040
	ds_read_b128 v[214:217], v140 offset:4608
	ds_read_b128 v[218:221], v140 offset:32
	ds_read_b128 v[222:225], v141 offset:18464
	ds_read_b128 v[226:229], v141 offset:23072
	ds_read_b128 v[230:233], v140 offset:4640
	s_setprio 1
	s_waitcnt lgkmcnt(4)
	v_mfma_f32_32x32x16_bf16 v[50:65], v[198:201], v[202:205], v[50:65]
	v_mfma_f32_32x32x16_bf16 v[34:49], v[198:201], v[206:209], v[34:49]
	v_mfma_f32_32x32x16_bf16 v[18:33], v[214:217], v[202:205], v[18:33]
	v_mfma_f32_32x32x16_bf16 v[2:17], v[214:217], v[206:209], v[2:17]
	global_load_dwordx4 v[86:89], v[160:161], off offset:768
	global_load_dwordx4 v[98:101], v[162:163], off offset:768
	global_load_dwordx4 v[102:105], v[164:165], off offset:768
	global_load_dwordx4 v[110:113], v[166:167], off offset:768
	global_load_dwordx4 v[114:117], v[158:159], off offset:768
	global_load_dwordx4 v[118:121], v[168:169], off offset:768
	global_load_dwordx4 v[122:125], v[170:171], off offset:768
	global_load_dwordx4 v[126:129], v[172:173], off offset:768
	ds_read_b128 v[198:201], v140 offset:64
	ds_read_b128 v[202:205], v141 offset:18496
	ds_read_b128 v[206:209], v141 offset:23104
	ds_read_b128 v[214:217], v140 offset:4672
	s_waitcnt lgkmcnt(4)
	v_mfma_f32_32x32x16_bf16 v[50:65], v[218:221], v[222:225], v[50:65]
	v_mfma_f32_32x32x16_bf16 v[34:49], v[218:221], v[226:229], v[34:49]
	v_mfma_f32_32x32x16_bf16 v[18:33], v[230:233], v[222:225], v[18:33]
	v_mfma_f32_32x32x16_bf16 v[2:17], v[230:233], v[226:229], v[2:17]
	ds_read_b128 v[218:221], v140 offset:96
	ds_read_b128 v[222:225], v141 offset:18528
	ds_read_b128 v[226:229], v141 offset:23136
	ds_read_b128 v[230:233], v140 offset:4704
	s_waitcnt lgkmcnt(4)
	v_mfma_f32_32x32x16_bf16 v[50:65], v[198:201], v[202:205], v[50:65]
	v_mfma_f32_32x32x16_bf16 v[34:49], v[198:201], v[206:209], v[34:49]
	v_mfma_f32_32x32x16_bf16 v[18:33], v[214:217], v[202:205], v[18:33]
	v_mfma_f32_32x32x16_bf16 v[2:17], v[214:217], v[206:209], v[2:17]
	s_waitcnt lgkmcnt(0)
	v_mfma_f32_32x32x16_bf16 v[50:65], v[218:221], v[222:225], v[50:65]
	v_mfma_f32_32x32x16_bf16 v[34:49], v[218:221], v[226:229], v[34:49]
	v_mfma_f32_32x32x16_bf16 v[18:33], v[230:233], v[222:225], v[18:33]
	v_mfma_f32_32x32x16_bf16 v[2:17], v[230:233], v[226:229], v[2:17]
	s_setprio 0
	s_waitcnt vmcnt(8)
	ds_write_b128 v188, v[66:69] offset:36864
	ds_write_b128 v188, v[70:73] offset:41472
	ds_write_b128 v188, v[74:77] offset:46080
	ds_write_b128 v188, v[78:81] offset:50688
	ds_write_b128 v188, v[82:85] offset:55296
	ds_write_b128 v188, v[90:93] offset:59904
	ds_write_b128 v188, v[94:97] offset:64512
	ds_write_b128 v189, v[106:109] offset:13824
	s_waitcnt lgkmcnt(0)
	s_barrier
; __device__ __forceinline__ void gemm_kstep(const u16* sb, int wn, int wt, int r, int h, f32x16 (&acc)[2][2]) {
;   const u16* bw = sb + (wn * 64 + r) * LDT + h * 8;
;   const u16* bx = sb + TILE_U16 + (wt * 64 + r) * LDT + h * 8;
;   __builtin_amdgcn_s_setprio(1);
; #pragma unroll
;   for (int ks = 0; ks < 4; ++ks) {
;     bf16x8 a0 = *(const bf16x8*)(bw + ks * 16);
;     bf16x8 a1 = *(const bf16x8*)(bw + 32 * LDT + ks * 16);
;     bf16x8 b0 = *(const bf16x8*)(bx + ks * 16);
;     bf16x8 b1 = *(const bf16x8*)(bx + 32 * LDT + ks * 16);
;     acc[0][0] = mfma32(a0, b0, acc[0][0]);
;     acc[0][1] = mfma32(a0, b1, acc[0][1]);
;     acc[1][0] = mfma32(a1, b0, acc[1][0]);
;     acc[1][1] = mfma32(a1, b1, acc[1][1]);
;   }
;   __builtin_amdgcn_s_setprio(0);
; }
; __device__ void gemm_phase(const u16* __restrict__ Wb, int ldw, const u16* __restrict__ Xb, int ldx, int K,
;                            u16* __restrict__ outb, int ldo, int ntn, int ntiles, u16* lds) {
;     ...
;     for (int kt = 0; kt < nk; kt += 2) {
;       if (kt + 2 < nk) gs_load(B, gw, ldw, gx, ldx, (kt + 2) * 64);
;       else if (has_next) gs_load(B, gwn, ldw, gxn, ldx, 0);
;       gemm_kstep(lds, wn, wt, r, h, acc);
;       gs_store(A, lds + 2 * TILE_U16, lo);
;       __syncthreads();
;       if (kt + 3 < nk) gs_load(A, gw, ldw, gx, ldx, (kt + 3) * 64);
;       else if (has_next) gs_load(A, gwn, ldw, gxn, ldx, 64);
;       gemm_kstep(lds + 2 * TILE_U16, wn, wt, r, h, acc);
;       if (kt + 2 < nk) gs_store(B, lds, lo);
;       __syncthreads();
;     }
	ds_read_b128 v[198:201], v140 offset:36864
	ds_read_b128 v[202:205], v141 offset:55296
	ds_read_b128 v[206:209], v141 offset:59904
	ds_read_b128 v[214:217], v140 offset:41472
	ds_read_b128 v[218:221], v140 offset:36896
	ds_read_b128 v[222:225], v141 offset:55328
	ds_read_b128 v[226:229], v141 offset:59936
	ds_read_b128 v[230:233], v140 offset:41504
	s_setprio 1
	s_waitcnt lgkmcnt(4)
	v_mfma_f32_32x32x16_bf16 v[50:65], v[198:201], v[202:205], v[50:65]
	v_mfma_f32_32x32x16_bf16 v[34:49], v[198:201], v[206:209], v[34:49]
	v_mfma_f32_32x32x16_bf16 v[18:33], v[214:217], v[202:205], v[18:33]
	v_mfma_f32_32x32x16_bf16 v[2:17], v[214:217], v[206:209], v[2:17]
	global_load_dwordx4 v[66:69], v[160:161], off offset:896
	global_load_dwordx4 v[70:73], v[162:163], off offset:896
	global_load_dwordx4 v[74:77], v[164:165], off offset:896
	global_load_dwordx4 v[78:81], v[166:167], off offset:896
	global_load_dwordx4 v[82:85], v[158:159], off offset:896
	global_load_dwordx4 v[90:93], v[168:169], off offset:896
	global_load_dwordx4 v[94:97], v[170:171], off offset:896
	global_load_dwordx4 v[106:109], v[172:173], off offset:896
	ds_read_b128 v[198:201], v140 offset:36928
	ds_read_b128 v[202:205], v141 offset:55360
	ds_read_b128 v[206:209], v141 offset:59968
	ds_read_b128 v[214:217], v140 offset:41536
	s_waitcnt lgkmcnt(4)
	v_mfma_f32_32x32x16_bf16 v[50:65], v[218:221], v[222:225], v[50:65]
	v_mfma_f32_32x32x16_bf16 v[34:49], v[218:221], v[226:229], v[34:49]
	v_mfma_f32_32x32x16_bf16 v[18:33], v[230:233], v[222:225], v[18:33]
	v_mfma_f32_32x32x16_bf16 v[2:17], v[230:233], v[226:229], v[2:17]
	ds_read_b128 v[218:221], v140 offset:36960
	ds_read_b128 v[222:225], v141 offset:55392
	ds_read_b128 v[226:229], v141 offset:60000
	ds_read_b128 v[230:233], v140 offset:41568
	s_waitcnt lgkmcnt(4)
	v_mfma_f32_32x32x16_bf16 v[50:65], v[198:201], v[202:205], v[50:65]
	v_mfma_f32_32x32x16_bf16 v[34:49], v[198:201], v[206:209], v[34:49]
	v_mfma_f32_32x32x16_bf16 v[18:33], v[214:217], v[202:205], v[18:33]
	v_mfma_f32_32x32x16_bf16 v[2:17], v[214:217], v[206:209], v[2:17]
	s_waitcnt lgkmcnt(0)
	v_mfma_f32_32x32x16_bf16 v[50:65], v[218:221], v[222:225], v[50:65]
	v_mfma_f32_32x32x16_bf16 v[34:49], v[218:221], v[226:229], v[34:49]
	v_mfma_f32_32x32x16_bf16 v[18:33], v[230:233], v[222:225], v[18:33]
	v_mfma_f32_32x32x16_bf16 v[2:17], v[230:233], v[226:229], v[2:17]
	s_setprio 0
	s_waitcnt vmcnt(8)
	ds_write_b128 v188, v[86:89]
	ds_write_b128 v188, v[98:101] offset:4608
	ds_write_b128 v188, v[102:105] offset:9216
	ds_write_b128 v188, v[110:113] offset:13824
	ds_write_b128 v188, v[114:117] offset:18432
	ds_write_b128 v188, v[118:121] offset:23040
	ds_write_b128 v188, v[122:125] offset:27648
	ds_write_b128 v188, v[126:129] offset:32256
	s_waitcnt lgkmcnt(0)
	s_barrier
	ds_read_b128 v[198:201], v140
	ds_read_b128 v[202:205], v141 offset:18432
	ds_read_b128 v[206:209], v141 offset:23040
	ds_read_b128 v[214:217], v140 offset:4608
	ds_read_b128 v[218:221], v140 offset:32
	ds_read_b128 v[222:225], v141 offset:18464
	ds_read_b128 v[226:229], v141 offset:23072
	ds_read_b128 v[230:233], v140 offset:4640
	s_setprio 1
	s_waitcnt lgkmcnt(4)
	v_mfma_f32_32x32x16_bf16 v[50:65], v[198:201], v[202:205], v[50:65]
	v_mfma_f32_32x32x16_bf16 v[34:49], v[198:201], v[206:209], v[34:49]
	v_mfma_f32_32x32x16_bf16 v[18:33], v[214:217], v[202:205], v[18:33]
	v_mfma_f32_32x32x16_bf16 v[2:17], v[214:217], v[206:209], v[2:17]
	global_load_dwordx4 v[86:89], v[160:161], off offset:1024
	global_load_dwordx4 v[98:101], v[162:163], off offset:1024
	global_load_dwordx4 v[102:105], v[164:165], off offset:1024
	global_load_dwordx4 v[110:113], v[166:167], off offset:1024
	global_load_dwordx4 v[114:117], v[158:159], off offset:1024
	global_load_dwordx4 v[118:121], v[168:169], off offset:1024
	global_load_dwordx4 v[122:125], v[170:171], off offset:1024
	global_load_dwordx4 v[126:129], v[172:173], off offset:1024
	ds_read_b128 v[198:201], v140 offset:64
	ds_read_b128 v[202:205], v141 offset:18496
	ds_read_b128 v[206:209], v141 offset:23104
	ds_read_b128 v[214:217], v140 offset:4672
	s_waitcnt lgkmcnt(4)
	v_mfma_f32_32x32x16_bf16 v[50:65], v[218:221], v[222:225], v[50:65]
	v_mfma_f32_32x32x16_bf16 v[34:49], v[218:221], v[226:229], v[34:49]
	v_mfma_f32_32x32x16_bf16 v[18:33], v[230:233], v[222:225], v[18:33]
	v_mfma_f32_32x32x16_bf16 v[2:17], v[230:233], v[226:229], v[2:17]
	ds_read_b128 v[218:221], v140 offset:96
	ds_read_b128 v[222:225], v141 offset:18528
	ds_read_b128 v[226:229], v141 offset:23136
	ds_read_b128 v[230:233], v140 offset:4704
	s_waitcnt lgkmcnt(4)
	v_mfma_f32_32x32x16_bf16 v[50:65], v[198:201], v[202:205], v[50:65]
	v_mfma_f32_32x32x16_bf16 v[34:49], v[198:201], v[206:209], v[34:49]
	v_mfma_f32_32x32x16_bf16 v[18:33], v[214:217], v[202:205], v[18:33]
	v_mfma_f32_32x32x16_bf16 v[2:17], v[214:217], v[206:209], v[2:17]
	s_waitcnt lgkmcnt(0)
	v_mfma_f32_32x32x16_bf16 v[50:65], v[218:221], v[222:225], v[50:65]
	v_mfma_f32_32x32x16_bf16 v[34:49], v[218:221], v[226:229], v[34:49]
	v_mfma_f32_32x32x16_bf16 v[18:33], v[230:233], v[222:225], v[18:33]
	v_mfma_f32_32x32x16_bf16 v[2:17], v[230:233], v[226:229], v[2:17]
	s_setprio 0
	s_waitcnt vmcnt(8)
	ds_write_b128 v188, v[66:69] offset:36864
	ds_write_b128 v188, v[70:73] offset:41472
	ds_write_b128 v188, v[74:77] offset:46080
	ds_write_b128 v188, v[78:81] offset:50688
	ds_write_b128 v188, v[82:85] offset:55296
	ds_write_b128 v188, v[90:93] offset:59904
	ds_write_b128 v188, v[94:97] offset:64512
	ds_write_b128 v189, v[106:109] offset:13824
	s_waitcnt lgkmcnt(0)
	s_barrier
; __device__ __forceinline__ void gemm_kstep(const u16* sb, int wn, int wt, int r, int h, f32x16 (&acc)[2][2]) {
;   const u16* bw = sb + (wn * 64 + r) * LDT + h * 8;
;   const u16* bx = sb + TILE_U16 + (wt * 64 + r) * LDT + h * 8;
;   __builtin_amdgcn_s_setprio(1);
; #pragma unroll
;   for (int ks = 0; ks < 4; ++ks) {
;     bf16x8 a0 = *(const bf16x8*)(bw + ks * 16);
;     bf16x8 a1 = *(const bf16x8*)(bw + 32 * LDT + ks * 16);
;     bf16x8 b0 = *(const bf16x8*)(bx + ks * 16);
;     bf16x8 b1 = *(const bf16x8*)(bx + 32 * LDT + ks * 16);
;     acc[0][0] = mfma32(a0, b0, acc[0][0]);
;     acc[0][1] = mfma32(a0, b1, acc[0][1]);
;     acc[1][0] = mfma32(a1, b0, acc[1][0]);
;     acc[1][1] = mfma32(a1, b1, acc[1][1]);
;   }
;   __builtin_amdgcn_s_setprio(0);
; }
; __device__ void gemm_phase(const u16* __restrict__ Wb, int ldw, const u16* __restrict__ Xb, int ldx, int K,
;                            u16* __restrict__ outb, int ldo, int ntn, int ntiles, u16* lds) {
;     ...
;     for (int kt = 0; kt < nk; kt += 2) {
;       if (kt + 2 < nk) gs_load(B, gw, ldw, gx, ldx, (kt + 2) * 64);
;       else if (has_next) gs_load(B, gwn, ldw, gxn, ldx, 0);
;       gemm_kstep(lds, wn, wt, r, h, acc);
;       gs_store(A, lds + 2 * TILE_U16, lo);
;       __syncthreads();
;       if (kt + 3 < nk) gs_load(A, gw, ldw, gx, ldx, (kt + 3) * 64);
;       else if (has_next) gs_load(A, gwn, ldw, gxn, ldx, 64);
;       gemm_kstep(lds + 2 * TILE_U16, wn, wt, r, h, acc);
;       if (kt + 2 < nk) gs_store(B, lds, lo);
;       __syncthreads();
;     }
	ds_read_b128 v[198:201], v140 offset:36864
	ds_read_b128 v[202:205], v141 offset:55296
	ds_read_b128 v[206:209], v141 offset:59904
	ds_read_b128 v[214:217], v140 offset:41472
	ds_read_b128 v[218:221], v140 offset:36896
	ds_read_b128 v[222:225], v141 offset:55328
	ds_read_b128 v[226:229], v141 offset:59936
	ds_read_b128 v[230:233], v140 offset:41504
	s_setprio 1
	s_waitcnt lgkmcnt(4)
	v_mfma_f32_32x32x16_bf16 v[50:65], v[198:201], v[202:205], v[50:65]
	v_mfma_f32_32x32x16_bf16 v[34:49], v[198:201], v[206:209], v[34:49]
	v_mfma_f32_32x32x16_bf16 v[18:33], v[214:217], v[202:205], v[18:33]
	v_mfma_f32_32x32x16_bf16 v[2:17], v[214:217], v[206:209], v[2:17]
	global_load_dwordx4 v[66:69], v[160:161], off offset:1152
	global_load_dwordx4 v[70:73], v[162:163], off offset:1152
	global_load_dwordx4 v[74:77], v[164:165], off offset:1152
	global_load_dwordx4 v[78:81], v[166:167], off offset:1152
	global_load_dwordx4 v[82:85], v[158:159], off offset:1152
	global_load_dwordx4 v[90:93], v[168:169], off offset:1152
	global_load_dwordx4 v[94:97], v[170:171], off offset:1152
	global_load_dwordx4 v[106:109], v[172:173], off offset:1152
	ds_read_b128 v[198:201], v140 offset:36928
	ds_read_b128 v[202:205], v141 offset:55360
	ds_read_b128 v[206:209], v141 offset:59968
	ds_read_b128 v[214:217], v140 offset:41536
	s_waitcnt lgkmcnt(4)
	v_mfma_f32_32x32x16_bf16 v[50:65], v[218:221], v[222:225], v[50:65]
	v_mfma_f32_32x32x16_bf16 v[34:49], v[218:221], v[226:229], v[34:49]
	v_mfma_f32_32x32x16_bf16 v[18:33], v[230:233], v[222:225], v[18:33]
	v_mfma_f32_32x32x16_bf16 v[2:17], v[230:233], v[226:229], v[2:17]
	ds_read_b128 v[218:221], v140 offset:36960
	ds_read_b128 v[222:225], v141 offset:55392
	ds_read_b128 v[226:229], v141 offset:60000
	ds_read_b128 v[230:233], v140 offset:41568
	s_waitcnt lgkmcnt(4)
	v_mfma_f32_32x32x16_bf16 v[50:65], v[198:201], v[202:205], v[50:65]
	v_mfma_f32_32x32x16_bf16 v[34:49], v[198:201], v[206:209], v[34:49]
	v_mfma_f32_32x32x16_bf16 v[18:33], v[214:217], v[202:205], v[18:33]
	v_mfma_f32_32x32x16_bf16 v[2:17], v[214:217], v[206:209], v[2:17]
	s_waitcnt lgkmcnt(0)
	v_mfma_f32_32x32x16_bf16 v[50:65], v[218:221], v[222:225], v[50:65]
	v_mfma_f32_32x32x16_bf16 v[34:49], v[218:221], v[226:229], v[34:49]
	v_mfma_f32_32x32x16_bf16 v[18:33], v[230:233], v[222:225], v[18:33]
	v_mfma_f32_32x32x16_bf16 v[2:17], v[230:233], v[226:229], v[2:17]
	s_setprio 0
	s_waitcnt vmcnt(8)
	ds_write_b128 v188, v[86:89]
	ds_write_b128 v188, v[98:101] offset:4608
	ds_write_b128 v188, v[102:105] offset:9216
	ds_write_b128 v188, v[110:113] offset:13824
	ds_write_b128 v188, v[114:117] offset:18432
	ds_write_b128 v188, v[118:121] offset:23040
	ds_write_b128 v188, v[122:125] offset:27648
	ds_write_b128 v188, v[126:129] offset:32256
	s_waitcnt lgkmcnt(0)
	s_barrier
	ds_read_b128 v[198:201], v140
	ds_read_b128 v[202:205], v141 offset:18432
	ds_read_b128 v[206:209], v141 offset:23040
	ds_read_b128 v[214:217], v140 offset:4608
	ds_read_b128 v[218:221], v140 offset:32
	ds_read_b128 v[222:225], v141 offset:18464
	ds_read_b128 v[226:229], v141 offset:23072
	ds_read_b128 v[230:233], v140 offset:4640
	s_setprio 1
	s_waitcnt lgkmcnt(4)
	v_mfma_f32_32x32x16_bf16 v[50:65], v[198:201], v[202:205], v[50:65]
	v_mfma_f32_32x32x16_bf16 v[34:49], v[198:201], v[206:209], v[34:49]
	v_mfma_f32_32x32x16_bf16 v[18:33], v[214:217], v[202:205], v[18:33]
	v_mfma_f32_32x32x16_bf16 v[2:17], v[214:217], v[206:209], v[2:17]
	global_load_dwordx4 v[86:89], v[160:161], off offset:1280
	global_load_dwordx4 v[98:101], v[162:163], off offset:1280
	global_load_dwordx4 v[102:105], v[164:165], off offset:1280
	global_load_dwordx4 v[110:113], v[166:167], off offset:1280
	global_load_dwordx4 v[114:117], v[158:159], off offset:1280
	global_load_dwordx4 v[118:121], v[168:169], off offset:1280
	global_load_dwordx4 v[122:125], v[170:171], off offset:1280
	global_load_dwordx4 v[126:129], v[172:173], off offset:1280
	ds_read_b128 v[198:201], v140 offset:64
	ds_read_b128 v[202:205], v141 offset:18496
	ds_read_b128 v[206:209], v141 offset:23104
	ds_read_b128 v[214:217], v140 offset:4672
	s_waitcnt lgkmcnt(4)
	v_mfma_f32_32x32x16_bf16 v[50:65], v[218:221], v[222:225], v[50:65]
	v_mfma_f32_32x32x16_bf16 v[34:49], v[218:221], v[226:229], v[34:49]
	v_mfma_f32_32x32x16_bf16 v[18:33], v[230:233], v[222:225], v[18:33]
	v_mfma_f32_32x32x16_bf16 v[2:17], v[230:233], v[226:229], v[2:17]
	ds_read_b128 v[218:221], v140 offset:96
	ds_read_b128 v[222:225], v141 offset:18528
	ds_read_b128 v[226:229], v141 offset:23136
	ds_read_b128 v[230:233], v140 offset:4704
	s_waitcnt lgkmcnt(4)
	v_mfma_f32_32x32x16_bf16 v[50:65], v[198:201], v[202:205], v[50:65]
	v_mfma_f32_32x32x16_bf16 v[34:49], v[198:201], v[206:209], v[34:49]
	v_mfma_f32_32x32x16_bf16 v[18:33], v[214:217], v[202:205], v[18:33]
	v_mfma_f32_32x32x16_bf16 v[2:17], v[214:217], v[206:209], v[2:17]
	s_waitcnt lgkmcnt(0)
	v_mfma_f32_32x32x16_bf16 v[50:65], v[218:221], v[222:225], v[50:65]
	v_mfma_f32_32x32x16_bf16 v[34:49], v[218:221], v[226:229], v[34:49]
	v_mfma_f32_32x32x16_bf16 v[18:33], v[230:233], v[222:225], v[18:33]
	v_mfma_f32_32x32x16_bf16 v[2:17], v[230:233], v[226:229], v[2:17]
	s_setprio 0
	s_waitcnt vmcnt(8)
	ds_write_b128 v188, v[66:69] offset:36864
	ds_write_b128 v188, v[70:73] offset:41472
	ds_write_b128 v188, v[74:77] offset:46080
	ds_write_b128 v188, v[78:81] offset:50688
	ds_write_b128 v188, v[82:85] offset:55296
	ds_write_b128 v188, v[90:93] offset:59904
	ds_write_b128 v188, v[94:97] offset:64512
	ds_write_b128 v189, v[106:109] offset:13824
	s_waitcnt lgkmcnt(0)
	s_barrier
; __device__ __forceinline__ void gemm_kstep(const u16* sb, int wn, int wt, int r, int h, f32x16 (&acc)[2][2]) {
;   const u16* bw = sb + (wn * 64 + r) * LDT + h * 8;
;   const u16* bx = sb + TILE_U16 + (wt * 64 + r) * LDT + h * 8;
;   __builtin_amdgcn_s_setprio(1);
; #pragma unroll
;   for (int ks = 0; ks < 4; ++ks) {
;     bf16x8 a0 = *(const bf16x8*)(bw + ks * 16);
;     bf16x8 a1 = *(const bf16x8*)(bw + 32 * LDT + ks * 16);
;     bf16x8 b0 = *(const bf16x8*)(bx + ks * 16);
;     bf16x8 b1 = *(const bf16x8*)(bx + 32 * LDT + ks * 16);
;     acc[0][0] = mfma32(a0, b0, acc[0][0]);
;     acc[0][1] = mfma32(a0, b1, acc[0][1]);
;     acc[1][0] = mfma32(a1, b0, acc[1][0]);
;     acc[1][1] = mfma32(a1, b1, acc[1][1]);
;   }
;   __builtin_amdgcn_s_setprio(0);
; }
; __device__ void gemm_phase(const u16* __restrict__ Wb, int ldw, const u16* __restrict__ Xb, int ldx, int K,
;                            u16* __restrict__ outb, int ldo, int ntn, int ntiles, u16* lds) {
;     ...
;     for (int kt = 0; kt < nk; kt += 2) {
;       if (kt + 2 < nk) gs_load(B, gw, ldw, gx, ldx, (kt + 2) * 64);
;       else if (has_next) gs_load(B, gwn, ldw, gxn, ldx, 0);
;       gemm_kstep(lds, wn, wt, r, h, acc);
;       gs_store(A, lds + 2 * TILE_U16, lo);
;       __syncthreads();
;       if (kt + 3 < nk) gs_load(A, gw, ldw, gx, ldx, (kt + 3) * 64);
;       else if (has_next) gs_load(A, gwn, ldw, gxn, ldx, 64);
;       gemm_kstep(lds + 2 * TILE_U16, wn, wt, r, h, acc);
;       if (kt + 2 < nk) gs_store(B, lds, lo);
;       __syncthreads();
;     }
	ds_read_b128 v[198:201], v140 offset:36864
	ds_read_b128 v[202:205], v141 offset:55296
	ds_read_b128 v[206:209], v141 offset:59904
	ds_read_b128 v[214:217], v140 offset:41472
	ds_read_b128 v[218:221], v140 offset:36896
	ds_read_b128 v[222:225], v141 offset:55328
	ds_read_b128 v[226:229], v141 offset:59936
	ds_read_b128 v[230:233], v140 offset:41504
	s_setprio 1
	s_waitcnt lgkmcnt(4)
	v_mfma_f32_32x32x16_bf16 v[50:65], v[198:201], v[202:205], v[50:65]
	v_mfma_f32_32x32x16_bf16 v[34:49], v[198:201], v[206:209], v[34:49]
	v_mfma_f32_32x32x16_bf16 v[18:33], v[214:217], v[202:205], v[18:33]
	v_mfma_f32_32x32x16_bf16 v[2:17], v[214:217], v[206:209], v[2:17]
	global_load_dwordx4 v[66:69], v[160:161], off offset:1408
	global_load_dwordx4 v[70:73], v[162:163], off offset:1408
	global_load_dwordx4 v[74:77], v[164:165], off offset:1408
	global_load_dwordx4 v[78:81], v[166:167], off offset:1408
	global_load_dwordx4 v[82:85], v[158:159], off offset:1408
	global_load_dwordx4 v[90:93], v[168:169], off offset:1408
	global_load_dwordx4 v[94:97], v[170:171], off offset:1408
	global_load_dwordx4 v[106:109], v[172:173], off offset:1408
	ds_read_b128 v[198:201], v140 offset:36928
	ds_read_b128 v[202:205], v141 offset:55360
	ds_read_b128 v[206:209], v141 offset:59968
	ds_read_b128 v[214:217], v140 offset:41536
	s_waitcnt lgkmcnt(4)
	v_mfma_f32_32x32x16_bf16 v[50:65], v[218:221], v[222:225], v[50:65]
	v_mfma_f32_32x32x16_bf16 v[34:49], v[218:221], v[226:229], v[34:49]
	v_mfma_f32_32x32x16_bf16 v[18:33], v[230:233], v[222:225], v[18:33]
	v_mfma_f32_32x32x16_bf16 v[2:17], v[230:233], v[226:229], v[2:17]
	ds_read_b128 v[218:221], v140 offset:36960
	ds_read_b128 v[222:225], v141 offset:55392
	ds_read_b128 v[226:229], v141 offset:60000
	ds_read_b128 v[230:233], v140 offset:41568
	s_waitcnt lgkmcnt(4)
	v_mfma_f32_32x32x16_bf16 v[50:65], v[198:201], v[202:205], v[50:65]
	v_mfma_f32_32x32x16_bf16 v[34:49], v[198:201], v[206:209], v[34:49]
	v_mfma_f32_32x32x16_bf16 v[18:33], v[214:217], v[202:205], v[18:33]
	v_mfma_f32_32x32x16_bf16 v[2:17], v[214:217], v[206:209], v[2:17]
	s_waitcnt lgkmcnt(0)
	v_mfma_f32_32x32x16_bf16 v[50:65], v[218:221], v[222:225], v[50:65]
	v_mfma_f32_32x32x16_bf16 v[34:49], v[218:221], v[226:229], v[34:49]
	v_mfma_f32_32x32x16_bf16 v[18:33], v[230:233], v[222:225], v[18:33]
	v_mfma_f32_32x32x16_bf16 v[2:17], v[230:233], v[226:229], v[2:17]
	s_setprio 0
	s_waitcnt vmcnt(8)
	ds_write_b128 v188, v[86:89]
	ds_write_b128 v188, v[98:101] offset:4608
	ds_write_b128 v188, v[102:105] offset:9216
	ds_write_b128 v188, v[110:113] offset:13824
	ds_write_b128 v188, v[114:117] offset:18432
	ds_write_b128 v188, v[118:121] offset:23040
	ds_write_b128 v188, v[122:125] offset:27648
	ds_write_b128 v188, v[126:129] offset:32256
	s_waitcnt lgkmcnt(0)
	s_barrier
	ds_read_b128 v[198:201], v140
	ds_read_b128 v[202:205], v141 offset:18432
	ds_read_b128 v[206:209], v141 offset:23040
	ds_read_b128 v[214:217], v140 offset:4608
	ds_read_b128 v[218:221], v140 offset:32
	ds_read_b128 v[222:225], v141 offset:18464
	ds_read_b128 v[226:229], v141 offset:23072
	ds_read_b128 v[230:233], v140 offset:4640
	s_setprio 1
	s_waitcnt lgkmcnt(4)
	v_mfma_f32_32x32x16_bf16 v[50:65], v[198:201], v[202:205], v[50:65]
	v_mfma_f32_32x32x16_bf16 v[34:49], v[198:201], v[206:209], v[34:49]
	v_mfma_f32_32x32x16_bf16 v[18:33], v[214:217], v[202:205], v[18:33]
	v_mfma_f32_32x32x16_bf16 v[2:17], v[214:217], v[206:209], v[2:17]
	global_load_dwordx4 v[86:89], v[160:161], off offset:1536
	global_load_dwordx4 v[98:101], v[162:163], off offset:1536
	global_load_dwordx4 v[102:105], v[164:165], off offset:1536
	global_load_dwordx4 v[110:113], v[166:167], off offset:1536
	global_load_dwordx4 v[114:117], v[158:159], off offset:1536
	global_load_dwordx4 v[118:121], v[168:169], off offset:1536
	global_load_dwordx4 v[122:125], v[170:171], off offset:1536
	global_load_dwordx4 v[126:129], v[172:173], off offset:1536
	ds_read_b128 v[198:201], v140 offset:64
	ds_read_b128 v[202:205], v141 offset:18496
	ds_read_b128 v[206:209], v141 offset:23104
	ds_read_b128 v[214:217], v140 offset:4672
	s_waitcnt lgkmcnt(4)
	v_mfma_f32_32x32x16_bf16 v[50:65], v[218:221], v[222:225], v[50:65]
	v_mfma_f32_32x32x16_bf16 v[34:49], v[218:221], v[226:229], v[34:49]
	v_mfma_f32_32x32x16_bf16 v[18:33], v[230:233], v[222:225], v[18:33]
	v_mfma_f32_32x32x16_bf16 v[2:17], v[230:233], v[226:229], v[2:17]
	ds_read_b128 v[218:221], v140 offset:96
	ds_read_b128 v[222:225], v141 offset:18528
	ds_read_b128 v[226:229], v141 offset:23136
	ds_read_b128 v[230:233], v140 offset:4704
	s_waitcnt lgkmcnt(4)
	v_mfma_f32_32x32x16_bf16 v[50:65], v[198:201], v[202:205], v[50:65]
	v_mfma_f32_32x32x16_bf16 v[34:49], v[198:201], v[206:209], v[34:49]
	v_mfma_f32_32x32x16_bf16 v[18:33], v[214:217], v[202:205], v[18:33]
	v_mfma_f32_32x32x16_bf16 v[2:17], v[214:217], v[206:209], v[2:17]
	s_waitcnt lgkmcnt(0)
	v_mfma_f32_32x32x16_bf16 v[50:65], v[218:221], v[222:225], v[50:65]
	v_mfma_f32_32x32x16_bf16 v[34:49], v[218:221], v[226:229], v[34:49]
	v_mfma_f32_32x32x16_bf16 v[18:33], v[230:233], v[222:225], v[18:33]
	v_mfma_f32_32x32x16_bf16 v[2:17], v[230:233], v[226:229], v[2:17]
	s_setprio 0
	s_waitcnt vmcnt(8)
	ds_write_b128 v188, v[66:69] offset:36864
	ds_write_b128 v188, v[70:73] offset:41472
	ds_write_b128 v188, v[74:77] offset:46080
	ds_write_b128 v188, v[78:81] offset:50688
	ds_write_b128 v188, v[82:85] offset:55296
	ds_write_b128 v188, v[90:93] offset:59904
	ds_write_b128 v188, v[94:97] offset:64512
	ds_write_b128 v189, v[106:109] offset:13824
	s_waitcnt lgkmcnt(0)
	s_barrier
; __device__ __forceinline__ void gemm_kstep(const u16* sb, int wn, int wt, int r, int h, f32x16 (&acc)[2][2]) {
;   const u16* bw = sb + (wn * 64 + r) * LDT + h * 8;
;   const u16* bx = sb + TILE_U16 + (wt * 64 + r) * LDT + h * 8;
;   __builtin_amdgcn_s_setprio(1);
; #pragma unroll
;   for (int ks = 0; ks < 4; ++ks) {
;     bf16x8 a0 = *(const bf16x8*)(bw + ks * 16);
;     bf16x8 a1 = *(const bf16x8*)(bw + 32 * LDT + ks * 16);
;     bf16x8 b0 = *(const bf16x8*)(bx + ks * 16);
;     bf16x8 b1 = *(const bf16x8*)(bx + 32 * LDT + ks * 16);
;     acc[0][0] = mfma32(a0, b0, acc[0][0]);
;     acc[0][1] = mfma32(a0, b1, acc[0][1]);
;     acc[1][0] = mfma32(a1, b0, acc[1][0]);
;     acc[1][1] = mfma32(a1, b1, acc[1][1]);
;   }
;   __builtin_amdgcn_s_setprio(0);
; }
; __device__ void gemm_phase(const u16* __restrict__ Wb, int ldw, const u16* __restrict__ Xb, int ldx, int K,
;                            u16* __restrict__ outb, int ldo, int ntn, int ntiles, u16* lds) {
;     ...
;     for (int kt = 0; kt < nk; kt += 2) {
;       if (kt + 2 < nk) gs_load(B, gw, ldw, gx, ldx, (kt + 2) * 64);
;       else if (has_next) gs_load(B, gwn, ldw, gxn, ldx, 0);
;       gemm_kstep(lds, wn, wt, r, h, acc);
;       gs_store(A, lds + 2 * TILE_U16, lo);
;       __syncthreads();
;       if (kt + 3 < nk) gs_load(A, gw, ldw, gx, ldx, (kt + 3) * 64);
;       else if (has_next) gs_load(A, gwn, ldw, gxn, ldx, 64);
;       gemm_kstep(lds + 2 * TILE_U16, wn, wt, r, h, acc);
;       if (kt + 2 < nk) gs_store(B, lds, lo);
;       __syncthreads();
;     }
	ds_read_b128 v[198:201], v140 offset:36864
	ds_read_b128 v[202:205], v141 offset:55296
	ds_read_b128 v[206:209], v141 offset:59904
	ds_read_b128 v[214:217], v140 offset:41472
	ds_read_b128 v[218:221], v140 offset:36896
	ds_read_b128 v[222:225], v141 offset:55328
	ds_read_b128 v[226:229], v141 offset:59936
	ds_read_b128 v[230:233], v140 offset:41504
	s_setprio 1
	s_waitcnt lgkmcnt(4)
	v_mfma_f32_32x32x16_bf16 v[50:65], v[198:201], v[202:205], v[50:65]
	v_mfma_f32_32x32x16_bf16 v[34:49], v[198:201], v[206:209], v[34:49]
	v_mfma_f32_32x32x16_bf16 v[18:33], v[214:217], v[202:205], v[18:33]
	v_mfma_f32_32x32x16_bf16 v[2:17], v[214:217], v[206:209], v[2:17]
	global_load_dwordx4 v[66:69], v[160:161], off offset:1664
	global_load_dwordx4 v[70:73], v[162:163], off offset:1664
	global_load_dwordx4 v[74:77], v[164:165], off offset:1664
	global_load_dwordx4 v[78:81], v[166:167], off offset:1664
	global_load_dwordx4 v[82:85], v[158:159], off offset:1664
	global_load_dwordx4 v[90:93], v[168:169], off offset:1664
	global_load_dwordx4 v[94:97], v[170:171], off offset:1664
	global_load_dwordx4 v[106:109], v[172:173], off offset:1664
	ds_read_b128 v[198:201], v140 offset:36928
	ds_read_b128 v[202:205], v141 offset:55360
	ds_read_b128 v[206:209], v141 offset:59968
	ds_read_b128 v[214:217], v140 offset:41536
	s_waitcnt lgkmcnt(4)
	v_mfma_f32_32x32x16_bf16 v[50:65], v[218:221], v[222:225], v[50:65]
	v_mfma_f32_32x32x16_bf16 v[34:49], v[218:221], v[226:229], v[34:49]
	v_mfma_f32_32x32x16_bf16 v[18:33], v[230:233], v[222:225], v[18:33]
	v_mfma_f32_32x32x16_bf16 v[2:17], v[230:233], v[226:229], v[2:17]
	ds_read_b128 v[218:221], v140 offset:36960
	ds_read_b128 v[222:225], v141 offset:55392
	ds_read_b128 v[226:229], v141 offset:60000
	ds_read_b128 v[230:233], v140 offset:41568
	s_waitcnt lgkmcnt(4)
	v_mfma_f32_32x32x16_bf16 v[50:65], v[198:201], v[202:205], v[50:65]
	v_mfma_f32_32x32x16_bf16 v[34:49], v[198:201], v[206:209], v[34:49]
	v_mfma_f32_32x32x16_bf16 v[18:33], v[214:217], v[202:205], v[18:33]
	v_mfma_f32_32x32x16_bf16 v[2:17], v[214:217], v[206:209], v[2:17]
	s_waitcnt lgkmcnt(0)
	v_mfma_f32_32x32x16_bf16 v[50:65], v[218:221], v[222:225], v[50:65]
	v_mfma_f32_32x32x16_bf16 v[34:49], v[218:221], v[226:229], v[34:49]
	v_mfma_f32_32x32x16_bf16 v[18:33], v[230:233], v[222:225], v[18:33]
	v_mfma_f32_32x32x16_bf16 v[2:17], v[230:233], v[226:229], v[2:17]
	s_setprio 0
	s_waitcnt vmcnt(8)
	ds_write_b128 v188, v[86:89]
	ds_write_b128 v188, v[98:101] offset:4608
	ds_write_b128 v188, v[102:105] offset:9216
	ds_write_b128 v188, v[110:113] offset:13824
	ds_write_b128 v188, v[114:117] offset:18432
	ds_write_b128 v188, v[118:121] offset:23040
	ds_write_b128 v188, v[122:125] offset:27648
	ds_write_b128 v188, v[126:129] offset:32256
	s_waitcnt lgkmcnt(0)
	s_barrier
	ds_read_b128 v[198:201], v140
	ds_read_b128 v[202:205], v141 offset:18432
	ds_read_b128 v[206:209], v141 offset:23040
	ds_read_b128 v[214:217], v140 offset:4608
	ds_read_b128 v[218:221], v140 offset:32
	ds_read_b128 v[222:225], v141 offset:18464
	ds_read_b128 v[226:229], v141 offset:23072
	ds_read_b128 v[230:233], v140 offset:4640
	s_setprio 1
	s_waitcnt lgkmcnt(4)
	v_mfma_f32_32x32x16_bf16 v[50:65], v[198:201], v[202:205], v[50:65]
	v_mfma_f32_32x32x16_bf16 v[34:49], v[198:201], v[206:209], v[34:49]
	v_mfma_f32_32x32x16_bf16 v[18:33], v[214:217], v[202:205], v[18:33]
	v_mfma_f32_32x32x16_bf16 v[2:17], v[214:217], v[206:209], v[2:17]
	global_load_dwordx4 v[86:89], v[160:161], off offset:1792
	global_load_dwordx4 v[98:101], v[162:163], off offset:1792
	global_load_dwordx4 v[102:105], v[164:165], off offset:1792
	global_load_dwordx4 v[110:113], v[166:167], off offset:1792
	global_load_dwordx4 v[114:117], v[158:159], off offset:1792
	global_load_dwordx4 v[118:121], v[168:169], off offset:1792
	global_load_dwordx4 v[122:125], v[170:171], off offset:1792
	global_load_dwordx4 v[126:129], v[172:173], off offset:1792
	ds_read_b128 v[198:201], v140 offset:64
	ds_read_b128 v[202:205], v141 offset:18496
	ds_read_b128 v[206:209], v141 offset:23104
	ds_read_b128 v[214:217], v140 offset:4672
	s_waitcnt lgkmcnt(4)
	v_mfma_f32_32x32x16_bf16 v[50:65], v[218:221], v[222:225], v[50:65]
	v_mfma_f32_32x32x16_bf16 v[34:49], v[218:221], v[226:229], v[34:49]
	v_mfma_f32_32x32x16_bf16 v[18:33], v[230:233], v[222:225], v[18:33]
	v_mfma_f32_32x32x16_bf16 v[2:17], v[230:233], v[226:229], v[2:17]
	ds_read_b128 v[218:221], v140 offset:96
	ds_read_b128 v[222:225], v141 offset:18528
	ds_read_b128 v[226:229], v141 offset:23136
	ds_read_b128 v[230:233], v140 offset:4704
	s_waitcnt lgkmcnt(4)
	v_mfma_f32_32x32x16_bf16 v[50:65], v[198:201], v[202:205], v[50:65]
	v_mfma_f32_32x32x16_bf16 v[34:49], v[198:201], v[206:209], v[34:49]
	v_mfma_f32_32x32x16_bf16 v[18:33], v[214:217], v[202:205], v[18:33]
	v_mfma_f32_32x32x16_bf16 v[2:17], v[214:217], v[206:209], v[2:17]
	s_waitcnt lgkmcnt(0)
	v_mfma_f32_32x32x16_bf16 v[50:65], v[218:221], v[222:225], v[50:65]
	v_mfma_f32_32x32x16_bf16 v[34:49], v[218:221], v[226:229], v[34:49]
	v_mfma_f32_32x32x16_bf16 v[18:33], v[230:233], v[222:225], v[18:33]
	v_mfma_f32_32x32x16_bf16 v[2:17], v[230:233], v[226:229], v[2:17]
	s_setprio 0
	s_waitcnt vmcnt(8)
	ds_write_b128 v188, v[66:69] offset:36864
	ds_write_b128 v188, v[70:73] offset:41472
	ds_write_b128 v188, v[74:77] offset:46080
	ds_write_b128 v188, v[78:81] offset:50688
	ds_write_b128 v188, v[82:85] offset:55296
	ds_write_b128 v188, v[90:93] offset:59904
	ds_write_b128 v188, v[94:97] offset:64512
	ds_write_b128 v189, v[106:109] offset:13824
	s_waitcnt lgkmcnt(0)
	s_barrier
; __device__ __forceinline__ void gemm_kstep(const u16* sb, int wn, int wt, int r, int h, f32x16 (&acc)[2][2]) {
;   const u16* bw = sb + (wn * 64 + r) * LDT + h * 8;
;   const u16* bx = sb + TILE_U16 + (wt * 64 + r) * LDT + h * 8;
;   __builtin_amdgcn_s_setprio(1);
; #pragma unroll
;   for (int ks = 0; ks < 4; ++ks) {
;     bf16x8 a0 = *(const bf16x8*)(bw + ks * 16);
;     bf16x8 a1 = *(const bf16x8*)(bw + 32 * LDT + ks * 16);
;     bf16x8 b0 = *(const bf16x8*)(bx + ks * 16);
;     bf16x8 b1 = *(const bf16x8*)(bx + 32 * LDT + ks * 16);
;     acc[0][0] = mfma32(a0, b0, acc[0][0]);
;     acc[0][1] = mfma32(a0, b1, acc[0][1]);
;     acc[1][0] = mfma32(a1, b0, acc[1][0]);
;     acc[1][1] = mfma32(a1, b1, acc[1][1]);
;   }
;   __builtin_amdgcn_s_setprio(0);
; }
; __device__ void gemm_phase(const u16* __restrict__ Wb, int ldw, const u16* __restrict__ Xb, int ldx, int K,
;                            u16* __restrict__ outb, int ldo, int ntn, int ntiles, u16* lds) {
;     ...
;     for (int kt = 0; kt < nk; kt += 2) {
;       if (kt + 2 < nk) gs_load(B, gw, ldw, gx, ldx, (kt + 2) * 64);
;       else if (has_next) gs_load(B, gwn, ldw, gxn, ldx, 0);
;       gemm_kstep(lds, wn, wt, r, h, acc);
;       gs_store(A, lds + 2 * TILE_U16, lo);
;       __syncthreads();
;       if (kt + 3 < nk) gs_load(A, gw, ldw, gx, ldx, (kt + 3) * 64);
;       else if (has_next) gs_load(A, gwn, ldw, gxn, ldx, 64);
;       gemm_kstep(lds + 2 * TILE_U16, wn, wt, r, h, acc);
;       if (kt + 2 < nk) gs_store(B, lds, lo);
;       __syncthreads();
;     }
	global_load_dwordx4 v[66:69], v[160:161], off offset:1920
	global_load_dwordx4 v[70:73], v[162:163], off offset:1920
	global_load_dwordx4 v[74:77], v[164:165], off offset:1920
	global_load_dwordx4 v[78:81], v[166:167], off offset:1920
	global_load_dwordx4 v[82:85], v[158:159], off offset:1920
	global_load_dwordx4 v[90:93], v[168:169], off offset:1920
	global_load_dwordx4 v[94:97], v[170:171], off offset:1920
	global_load_dwordx4 v[106:109], v[172:173], off offset:1920
	ds_read_b128 v[158:161], v140 offset:36864
	ds_read_b128 v[162:165], v141 offset:55296
	ds_read_b128 v[166:169], v141 offset:59904
	ds_read_b128 v[214:217], v140 offset:41472
	ds_read_b128 v[218:221], v140 offset:36896
	ds_read_b128 v[222:225], v141 offset:55328
	ds_read_b128 v[226:229], v141 offset:59936
	ds_read_b128 v[230:233], v140 offset:41504
	s_setprio 1
	s_waitcnt lgkmcnt(4)
	v_mfma_f32_32x32x16_bf16 v[50:65], v[158:161], v[162:165], v[50:65]
	v_mfma_f32_32x32x16_bf16 v[34:49], v[158:161], v[166:169], v[34:49]
	v_mfma_f32_32x32x16_bf16 v[18:33], v[214:217], v[162:165], v[18:33]
	v_mfma_f32_32x32x16_bf16 v[2:17], v[214:217], v[166:169], v[2:17]
	ds_read_b128 v[158:161], v140 offset:36928
	ds_read_b128 v[162:165], v141 offset:55360
	ds_read_b128 v[166:169], v141 offset:59968
	ds_read_b128 v[214:217], v140 offset:41536
	s_waitcnt lgkmcnt(4)
	v_mfma_f32_32x32x16_bf16 v[50:65], v[218:221], v[222:225], v[50:65]
	v_mfma_f32_32x32x16_bf16 v[34:49], v[218:221], v[226:229], v[34:49]
	v_mfma_f32_32x32x16_bf16 v[18:33], v[230:233], v[222:225], v[18:33]
	v_mfma_f32_32x32x16_bf16 v[2:17], v[230:233], v[226:229], v[2:17]
	ds_read_b128 v[218:221], v140 offset:36960
	ds_read_b128 v[222:225], v141 offset:55392
	ds_read_b128 v[226:229], v141 offset:60000
	ds_read_b128 v[230:233], v140 offset:41568
	s_waitcnt lgkmcnt(4)
	v_mfma_f32_32x32x16_bf16 v[50:65], v[158:161], v[162:165], v[50:65]
	v_mfma_f32_32x32x16_bf16 v[34:49], v[158:161], v[166:169], v[34:49]
	v_mfma_f32_32x32x16_bf16 v[18:33], v[214:217], v[162:165], v[18:33]
	v_mfma_f32_32x32x16_bf16 v[2:17], v[214:217], v[166:169], v[2:17]
	s_waitcnt lgkmcnt(0)
	v_mfma_f32_32x32x16_bf16 v[50:65], v[218:221], v[222:225], v[50:65]
	v_mfma_f32_32x32x16_bf16 v[34:49], v[218:221], v[226:229], v[34:49]
	v_mfma_f32_32x32x16_bf16 v[18:33], v[230:233], v[222:225], v[18:33]
	v_mfma_f32_32x32x16_bf16 v[2:17], v[230:233], v[226:229], v[2:17]
	s_setprio 0
	s_and_b64 vcc, exec, s[0:1]
	s_waitcnt vmcnt(8)
	ds_write_b128 v188, v[86:89]
	ds_write_b128 v188, v[98:101] offset:4608
	ds_write_b128 v188, v[102:105] offset:9216
	ds_write_b128 v188, v[110:113] offset:13824
	ds_write_b128 v188, v[114:117] offset:18432
	ds_write_b128 v188, v[118:121] offset:23040
	ds_write_b128 v188, v[122:125] offset:27648
	ds_write_b128 v188, v[126:129] offset:32256
	s_waitcnt lgkmcnt(0)
	s_barrier
	s_cbranch_vccnz .LBB0_611
	v_add_co_u32_e32 v98, vcc, 0x10000, v132
	global_load_dwordx4 v[86:89], v[132:133], off
	s_nop 0
	v_addc_co_u32_e32 v99, vcc, 0, v133, vcc
	v_add_co_u32_e32 v102, vcc, 0x20000, v132
	s_nop 1
	v_addc_co_u32_e32 v103, vcc, 0, v133, vcc
	v_add_co_u32_e32 v110, vcc, 0x30000, v132
	global_load_dwordx4 v[98:101], v[98:99], off
	s_nop 0
	global_load_dwordx4 v[102:105], v[102:103], off
	v_addc_co_u32_e32 v111, vcc, 0, v133, vcc
	v_add_co_u32_e32 v118, vcc, 0x10000, v134
	global_load_dwordx4 v[110:113], v[110:111], off
	s_nop 0
	global_load_dwordx4 v[114:117], v[134:135], off
	v_addc_co_u32_e32 v119, vcc, 0, v135, vcc
	v_add_co_u32_e32 v122, vcc, 0x20000, v134
	s_nop 1
	v_addc_co_u32_e32 v123, vcc, 0, v135, vcc
	v_add_co_u32_e32 v126, vcc, 0x30000, v134
	global_load_dwordx4 v[118:121], v[118:119], off
	s_nop 0
	global_load_dwordx4 v[122:125], v[122:123], off
	v_addc_co_u32_e32 v127, vcc, 0, v135, vcc
	global_load_dwordx4 v[126:129], v[126:127], off
; __device__ __forceinline__ void gemm_kstep(const u16* sb, int wn, int wt, int r, int h, f32x16 (&acc)[2][2]) {
;   const u16* bw = sb + (wn * 64 + r) * LDT + h * 8;
;   const u16* bx = sb + TILE_U16 + (wt * 64 + r) * LDT + h * 8;
;   __builtin_amdgcn_s_setprio(1);
; #pragma unroll
;   for (int ks = 0; ks < 4; ++ks) {
;     bf16x8 a0 = *(const bf16x8*)(bw + ks * 16);
;     bf16x8 a1 = *(const bf16x8*)(bw + 32 * LDT + ks * 16);
;     bf16x8 b0 = *(const bf16x8*)(bx + ks * 16);
;     bf16x8 b1 = *(const bf16x8*)(bx + 32 * LDT + ks * 16);
;     acc[0][0] = mfma32(a0, b0, acc[0][0]);
;     acc[0][1] = mfma32(a0, b1, acc[0][1]);
;     acc[1][0] = mfma32(a1, b0, acc[1][0]);
;     acc[1][1] = mfma32(a1, b1, acc[1][1]);
;   }
;   __builtin_amdgcn_s_setprio(0);
; }
; __device__ void gemm_phase(const u16* __restrict__ Wb, int ldw, const u16* __restrict__ Xb, int ldx, int K,
;                            u16* __restrict__ outb, int ldo, int ntn, int ntiles, u16* lds) {
;     ...
;     for (int kt = 0; kt < nk; kt += 2) {
;       if (kt + 2 < nk) gs_load(B, gw, ldw, gx, ldx, (kt + 2) * 64);
;       else if (has_next) gs_load(B, gwn, ldw, gxn, ldx, 0);
;       gemm_kstep(lds, wn, wt, r, h, acc);
;       gs_store(A, lds + 2 * TILE_U16, lo);
;       __syncthreads();
;       if (kt + 3 < nk) gs_load(A, gw, ldw, gx, ldx, (kt + 3) * 64);
;       else if (has_next) gs_load(A, gwn, ldw, gxn, ldx, 64);
;       gemm_kstep(lds + 2 * TILE_U16, wn, wt, r, h, acc);
;       if (kt + 2 < nk) gs_store(B, lds, lo);
;       __syncthreads();
;     }
.LBB0_611:
	ds_read_b128 v[158:161], v140
	ds_read_b128 v[162:165], v141 offset:18432
	ds_read_b128 v[166:169], v141 offset:23040
	ds_read_b128 v[214:217], v140 offset:4608
	ds_read_b128 v[218:221], v140 offset:32
	ds_read_b128 v[222:225], v141 offset:18464
	ds_read_b128 v[226:229], v141 offset:23072
	ds_read_b128 v[230:233], v140 offset:4640
	s_setprio 1
	s_waitcnt lgkmcnt(4)
	v_mfma_f32_32x32x16_bf16 v[50:65], v[158:161], v[162:165], v[50:65]
	v_mfma_f32_32x32x16_bf16 v[34:49], v[158:161], v[166:169], v[34:49]
	v_mfma_f32_32x32x16_bf16 v[18:33], v[214:217], v[162:165], v[18:33]
	v_mfma_f32_32x32x16_bf16 v[2:17], v[214:217], v[166:169], v[2:17]
	ds_read_b128 v[158:161], v140 offset:64
	ds_read_b128 v[162:165], v141 offset:18496
	ds_read_b128 v[166:169], v141 offset:23104
	ds_read_b128 v[214:217], v140 offset:4672
	s_waitcnt lgkmcnt(4)
	v_mfma_f32_32x32x16_bf16 v[50:65], v[218:221], v[222:225], v[50:65]
	v_mfma_f32_32x32x16_bf16 v[34:49], v[218:221], v[226:229], v[34:49]
	v_mfma_f32_32x32x16_bf16 v[18:33], v[230:233], v[222:225], v[18:33]
	v_mfma_f32_32x32x16_bf16 v[2:17], v[230:233], v[226:229], v[2:17]
	ds_read_b128 v[218:221], v140 offset:96
	ds_read_b128 v[222:225], v141 offset:18528
	ds_read_b128 v[226:229], v141 offset:23136
	ds_read_b128 v[230:233], v140 offset:4704
	s_waitcnt lgkmcnt(4)
	v_mfma_f32_32x32x16_bf16 v[50:65], v[158:161], v[162:165], v[50:65]
	v_mfma_f32_32x32x16_bf16 v[34:49], v[158:161], v[166:169], v[34:49]
	v_mfma_f32_32x32x16_bf16 v[18:33], v[214:217], v[162:165], v[18:33]
	v_mfma_f32_32x32x16_bf16 v[2:17], v[214:217], v[166:169], v[2:17]
	s_waitcnt lgkmcnt(0)
	v_mfma_f32_32x32x16_bf16 v[50:65], v[218:221], v[222:225], v[50:65]
	v_mfma_f32_32x32x16_bf16 v[34:49], v[218:221], v[226:229], v[34:49]
	v_mfma_f32_32x32x16_bf16 v[18:33], v[230:233], v[222:225], v[18:33]
	v_mfma_f32_32x32x16_bf16 v[2:17], v[230:233], v[226:229], v[2:17]
	s_setprio 0
	s_andn2_b64 vcc, exec, s[38:39]
	s_waitcnt vmcnt(7)
	ds_write_b128 v188, v[66:69] offset:36864
	s_waitcnt vmcnt(6)
	ds_write_b128 v188, v[70:73] offset:41472
	s_waitcnt vmcnt(5)
	ds_write_b128 v188, v[74:77] offset:46080
	s_waitcnt vmcnt(4)
	ds_write_b128 v188, v[78:81] offset:50688
	s_waitcnt vmcnt(3)
	ds_write_b128 v188, v[82:85] offset:55296
	s_waitcnt vmcnt(2)
	ds_write_b128 v188, v[90:93] offset:59904
	s_waitcnt vmcnt(1)
	ds_write_b128 v188, v[94:97] offset:64512
	s_waitcnt vmcnt(0)
	ds_write_b128 v189, v[106:109] offset:13824
	s_waitcnt lgkmcnt(0)
	s_barrier
	s_cbranch_vccnz .LBB0_608
	v_add_co_u32_e32 v70, vcc, 0x10000, v132
	global_load_dwordx4 v[66:69], v[132:133], off offset:128
	s_nop 0
	v_addc_co_u32_e32 v71, vcc, 0, v133, vcc
	v_add_co_u32_e32 v74, vcc, 0x20000, v132
	s_nop 1
	v_addc_co_u32_e32 v75, vcc, 0, v133, vcc
	v_add_co_u32_e32 v78, vcc, 0x30000, v132
	global_load_dwordx4 v[70:73], v[70:71], off offset:128
	s_nop 0
	global_load_dwordx4 v[74:77], v[74:75], off offset:128
	v_addc_co_u32_e32 v79, vcc, 0, v133, vcc
	v_add_co_u32_e32 v90, vcc, 0x10000, v134
	global_load_dwordx4 v[78:81], v[78:79], off offset:128
	s_nop 0
	global_load_dwordx4 v[82:85], v[134:135], off offset:128
	v_addc_co_u32_e32 v91, vcc, 0, v135, vcc
	v_add_co_u32_e32 v94, vcc, 0x20000, v134
	s_nop 1
	v_addc_co_u32_e32 v95, vcc, 0, v135, vcc
	v_add_co_u32_e32 v106, vcc, 0x30000, v134
	global_load_dwordx4 v[90:93], v[90:91], off offset:128
	s_nop 0
	global_load_dwordx4 v[94:97], v[94:95], off offset:128
	v_addc_co_u32_e32 v107, vcc, 0, v135, vcc
	global_load_dwordx4 v[106:109], v[106:107], off offset:128
	s_branch .LBB0_608
